# one static priority raise for the leading wave half (waves 0-3) per GEMM tile in the plain and swiglu GEMMs; all per-segment s_setprio flips removed
# baseline (speedup 1.0000x reference)
.LBB0_415:
	s_cmp_eq_u64 s[14:15], 0
	s_cbranch_scc1 .Lprio_skip_g1
	s_setprio 1
.Lprio_skip_g1:
	v_add_u32_e32 v244, 0x10000, v3
	v_writelane_b32 v250, s5, 0
	v_writelane_b32 v250, s23, 1
	v_writelane_b32 v250, s26, 2
	v_writelane_b32 v250, s27, 3
	v_writelane_b32 v250, s28, 4
	v_writelane_b32 v250, s29, 5
	v_writelane_b32 v250, s42, 6
	v_writelane_b32 v250, s43, 7
	v_writelane_b32 v250, s44, 8
	v_writelane_b32 v250, s45, 9
	v_writelane_b32 v250, s46, 10
	v_writelane_b32 v250, s47, 11
	v_writelane_b32 v250, s48, 12
	v_writelane_b32 v250, s49, 13
	v_writelane_b32 v250, s50, 14
	v_writelane_b32 v250, s51, 15
	v_writelane_b32 v250, s53, 16
	v_writelane_b32 v250, s54, 17
	v_writelane_b32 v250, s55, 18
	v_writelane_b32 v250, s56, 19
	v_writelane_b32 v250, s57, 20
	v_writelane_b32 v250, s58, 21
	v_writelane_b32 v250, s59, 22
	v_writelane_b32 v250, s60, 23
	v_writelane_b32 v250, s61, 24
	v_writelane_b32 v250, s63, 25
	v_writelane_b32 v250, s64, 26
	v_writelane_b32 v250, s65, 27
	s_add_i32 s53, s90, 0x80
	s_add_i32 s54, s52, -4
	s_add_i32 s55, s52, -3
	s_mov_b32 s56, s48
	s_add_i32 s57, s56, 0x2000
	s_add_i32 s58, s56, 0x4000
	s_add_i32 s59, s56, 0x6000
	s_add_i32 s60, s56, 0x8000
	s_add_i32 s61, s56, 0xa000
	v_readfirstlane_b32 s42, v6
	v_readfirstlane_b32 s43, v7
	v_readfirstlane_b32 s28, v4
	v_readfirstlane_b32 s29, v5
	v_readfirstlane_b32 s26, v146
	v_readfirstlane_b32 s5, v147
	v_readfirstlane_b32 s27, v148
	v_readfirstlane_b32 s23, v149
	s_add_u32 s28, s28, 0x100
	s_addc_u32 s29, s29, 0
	s_mov_b32 s63, -2
	v_mov_b32_e32 v4, 0
	s_add_u32 s44, s42, 0x100
	s_addc_u32 s45, s43, 0
	s_cmp_eq_u32 s63, s54
	s_cselect_b32 s50, s26, s44
	s_cselect_b32 s51, s5, s45
	s_cselect_b32 s48, s27, s28
	s_cselect_b32 s49, s23, s29
	s_add_u32 s46, s42, 0x80
	s_addc_u32 s47, s43, 0
	s_mov_b32 m0, s60
	s_add_u32 s42, s42, s53
	s_addc_u32 s43, s43, 0
	global_load_lds_dwordx4 v0, s[46:47]
	s_mov_b32 m0, s61
	ds_read_b128 v[164:167], v244
	global_load_lds_dwordx4 v142, s[46:47]
	ds_read_b128 v[168:171], v244 offset:1024
	ds_read_b128 v[188:191], v244 offset:2048
	ds_read_b128 v[192:195], v244 offset:3072
	ds_read_b128 v[196:199], v244 offset:16384
	ds_read_b128 v[200:203], v244 offset:17408
	ds_read_b128 v[204:207], v244 offset:18432
	ds_read_b128 v[208:211], v244 offset:19456
	s_add_i32 m0, s56, 0xc000
	ds_read_b128 v[212:215], v160
	global_load_lds_dwordx4 v0, s[42:43]
	s_add_i32 m0, s56, 0xe000
	ds_read_b128 v[216:219], v160 offset:1024
	global_load_lds_dwordx4 v142, s[42:43]
	ds_read_b128 v[220:223], v160 offset:2048
	ds_read_b128 v[224:227], v160 offset:3072
	ds_read_b128 v[228:231], v160 offset:4096
	ds_read_b128 v[232:235], v160 offset:5120
	ds_read_b128 v[236:239], v160 offset:6144
	ds_read_b128 v[240:243], v160 offset:7168
	s_waitcnt vmcnt(8)
	s_waitcnt lgkmcnt(8)
	s_barrier
	s_waitcnt lgkmcnt(0)
	v_mfma_f32_16x16x32_bf16 v[128:131], v[164:167], v[212:215], 0
	v_mfma_f32_16x16x32_bf16 v[124:127], v[188:191], v[212:215], 0
	v_mfma_f32_16x16x32_bf16 v[112:115], v[164:167], v[220:223], 0
	v_mfma_f32_16x16x32_bf16 v[108:111], v[188:191], v[220:223], 0
	v_mfma_f32_16x16x32_bf16 v[96:99], v[164:167], v[228:231], 0
	v_mfma_f32_16x16x32_bf16 v[92:95], v[188:191], v[228:231], 0
	v_mfma_f32_16x16x32_bf16 v[80:83], v[164:167], v[236:239], 0
	v_mfma_f32_16x16x32_bf16 v[76:79], v[188:191], v[236:239], 0
	v_mfma_f32_16x16x32_bf16 v[128:131], v[168:171], v[216:219], v[128:131]
	v_mfma_f32_16x16x32_bf16 v[124:127], v[192:195], v[216:219], v[124:127]
	v_mfma_f32_16x16x32_bf16 v[112:115], v[168:171], v[224:227], v[112:115]
	v_mfma_f32_16x16x32_bf16 v[108:111], v[192:195], v[224:227], v[108:111]
	v_mfma_f32_16x16x32_bf16 v[96:99], v[168:171], v[232:235], v[96:99]
	v_mfma_f32_16x16x32_bf16 v[92:95], v[192:195], v[232:235], v[92:95]
	v_mfma_f32_16x16x32_bf16 v[80:83], v[168:171], v[240:243], v[80:83]
	v_mfma_f32_16x16x32_bf16 v[76:79], v[192:195], v[240:243], v[76:79]
	v_mfma_f32_16x16x32_bf16 v[120:123], v[196:199], v[212:215], 0
	v_mfma_f32_16x16x32_bf16 v[116:119], v[204:207], v[212:215], 0
	v_mfma_f32_16x16x32_bf16 v[104:107], v[196:199], v[220:223], 0
	v_mfma_f32_16x16x32_bf16 v[100:103], v[204:207], v[220:223], 0
	v_mfma_f32_16x16x32_bf16 v[88:91], v[196:199], v[228:231], 0
	v_mfma_f32_16x16x32_bf16 v[84:87], v[204:207], v[228:231], 0
	v_mfma_f32_16x16x32_bf16 v[72:75], v[196:199], v[236:239], 0
	v_mfma_f32_16x16x32_bf16 v[68:71], v[204:207], v[236:239], 0
	v_mfma_f32_16x16x32_bf16 v[120:123], v[200:203], v[216:219], v[120:123]
	v_mfma_f32_16x16x32_bf16 v[116:119], v[208:211], v[216:219], v[116:119]
	v_mfma_f32_16x16x32_bf16 v[104:107], v[200:203], v[224:227], v[104:107]
	v_mfma_f32_16x16x32_bf16 v[100:103], v[208:211], v[224:227], v[100:103]
	v_mfma_f32_16x16x32_bf16 v[88:91], v[200:203], v[232:235], v[88:91]
	v_mfma_f32_16x16x32_bf16 v[84:87], v[208:211], v[232:235], v[84:87]
	v_mfma_f32_16x16x32_bf16 v[72:75], v[200:203], v[240:243], v[72:75]
	v_mfma_f32_16x16x32_bf16 v[68:71], v[208:211], v[240:243], v[68:71]
	s_barrier
	s_add_i32 m0, s69, 0x10000
	s_add_u32 s42, s48, s90
	s_addc_u32 s43, s49, 0
	global_load_lds_dwordx4 v140, s[48:49]
	s_add_i32 m0, s69, 0x12000
	ds_read_b128 v[212:215], v160 offset:16384
	global_load_lds_dwordx4 v144, s[48:49]
	s_add_i32 m0, s69, 0x14000
	ds_read_b128 v[216:219], v160 offset:17408
	global_load_lds_dwordx4 v140, s[42:43]
	s_add_i32 m0, s69, 0x16000
	ds_read_b128 v[220:223], v160 offset:18432
	global_load_lds_dwordx4 v144, s[42:43]
	ds_read_b128 v[224:227], v160 offset:19456
	ds_read_b128 v[228:231], v160 offset:20480
	ds_read_b128 v[232:235], v160 offset:21504
	ds_read_b128 v[236:239], v160 offset:22528
	ds_read_b128 v[240:243], v160 offset:23552
	s_waitcnt vmcnt(6)
	s_waitcnt lgkmcnt(0)
	s_barrier
	s_waitcnt lgkmcnt(0)
	v_mfma_f32_16x16x32_bf16 v[64:67], v[164:167], v[212:215], 0
	v_mfma_f32_16x16x32_bf16 v[60:63], v[188:191], v[212:215], 0
	v_mfma_f32_16x16x32_bf16 v[48:51], v[164:167], v[220:223], 0
	v_mfma_f32_16x16x32_bf16 v[44:47], v[188:191], v[220:223], 0
	v_mfma_f32_16x16x32_bf16 v[32:35], v[164:167], v[228:231], 0
	v_mfma_f32_16x16x32_bf16 v[28:31], v[188:191], v[228:231], 0
	v_mfma_f32_16x16x32_bf16 v[16:19], v[164:167], v[236:239], 0
	v_mfma_f32_16x16x32_bf16 v[12:15], v[188:191], v[236:239], 0
	v_mfma_f32_16x16x32_bf16 v[64:67], v[168:171], v[216:219], v[64:67]
	v_mfma_f32_16x16x32_bf16 v[60:63], v[192:195], v[216:219], v[60:63]
	v_mfma_f32_16x16x32_bf16 v[48:51], v[168:171], v[224:227], v[48:51]
	v_mfma_f32_16x16x32_bf16 v[44:47], v[192:195], v[224:227], v[44:47]
	v_mfma_f32_16x16x32_bf16 v[32:35], v[168:171], v[232:235], v[32:35]
	v_mfma_f32_16x16x32_bf16 v[28:31], v[192:195], v[232:235], v[28:31]
	v_mfma_f32_16x16x32_bf16 v[16:19], v[168:171], v[240:243], v[16:19]
	v_mfma_f32_16x16x32_bf16 v[12:15], v[192:195], v[240:243], v[12:15]
	v_mfma_f32_16x16x32_bf16 v[56:59], v[196:199], v[212:215], 0
	v_mfma_f32_16x16x32_bf16 v[52:55], v[204:207], v[212:215], 0
	v_mfma_f32_16x16x32_bf16 v[40:43], v[196:199], v[220:223], 0
	v_mfma_f32_16x16x32_bf16 v[36:39], v[204:207], v[220:223], 0
	v_mfma_f32_16x16x32_bf16 v[24:27], v[196:199], v[228:231], 0
	v_mfma_f32_16x16x32_bf16 v[20:23], v[204:207], v[228:231], 0
	v_mfma_f32_16x16x32_bf16 v[8:11], v[196:199], v[236:239], 0
	v_mfma_f32_16x16x32_bf16 v[4:7], v[204:207], v[236:239], 0
	v_mfma_f32_16x16x32_bf16 v[56:59], v[200:203], v[216:219], v[56:59]
	v_mfma_f32_16x16x32_bf16 v[52:55], v[208:211], v[216:219], v[52:55]
	v_mfma_f32_16x16x32_bf16 v[40:43], v[200:203], v[224:227], v[40:43]
	v_mfma_f32_16x16x32_bf16 v[36:39], v[208:211], v[224:227], v[36:39]
	v_mfma_f32_16x16x32_bf16 v[24:27], v[200:203], v[232:235], v[24:27]
	v_mfma_f32_16x16x32_bf16 v[20:23], v[208:211], v[232:235], v[20:23]
	v_mfma_f32_16x16x32_bf16 v[8:11], v[200:203], v[240:243], v[8:11]
	v_mfma_f32_16x16x32_bf16 v[4:7], v[208:211], v[240:243], v[4:7]
	s_barrier
	s_mov_b32 m0, s56
	s_add_u32 s42, s50, s90
	s_addc_u32 s43, s51, 0
	global_load_lds_dwordx4 v0, s[50:51]
	s_mov_b32 m0, s57
	ds_read_b128 v[164:167], v244 offset:32768
	global_load_lds_dwordx4 v142, s[50:51]
	ds_read_b128 v[168:171], v244 offset:33792
	ds_read_b128 v[188:191], v244 offset:34816
	ds_read_b128 v[192:195], v244 offset:35840
	ds_read_b128 v[196:199], v244 offset:49152
	ds_read_b128 v[200:203], v244 offset:50176
	ds_read_b128 v[204:207], v244 offset:51200
	ds_read_b128 v[208:211], v244 offset:52224
	s_mov_b32 m0, s58
	ds_read_b128 v[212:215], v160 offset:32768
	global_load_lds_dwordx4 v0, s[42:43]
	s_mov_b32 m0, s59
	ds_read_b128 v[216:219], v160 offset:33792
	global_load_lds_dwordx4 v142, s[42:43]
	ds_read_b128 v[220:223], v160 offset:34816
	ds_read_b128 v[224:227], v160 offset:35840
	ds_read_b128 v[228:231], v160 offset:36864
	ds_read_b128 v[232:235], v160 offset:37888
	ds_read_b128 v[236:239], v160 offset:38912
	ds_read_b128 v[240:243], v160 offset:39936
	s_waitcnt vmcnt(8)
	s_waitcnt lgkmcnt(8)
	s_barrier
	s_waitcnt lgkmcnt(0)
	v_mfma_f32_16x16x32_bf16 v[128:131], v[164:167], v[212:215], v[128:131]
	v_mfma_f32_16x16x32_bf16 v[124:127], v[188:191], v[212:215], v[124:127]
	v_mfma_f32_16x16x32_bf16 v[112:115], v[164:167], v[220:223], v[112:115]
	v_mfma_f32_16x16x32_bf16 v[108:111], v[188:191], v[220:223], v[108:111]
	v_mfma_f32_16x16x32_bf16 v[96:99], v[164:167], v[228:231], v[96:99]
	v_mfma_f32_16x16x32_bf16 v[92:95], v[188:191], v[228:231], v[92:95]
	v_mfma_f32_16x16x32_bf16 v[80:83], v[164:167], v[236:239], v[80:83]
	v_mfma_f32_16x16x32_bf16 v[76:79], v[188:191], v[236:239], v[76:79]
	v_mfma_f32_16x16x32_bf16 v[128:131], v[168:171], v[216:219], v[128:131]
	v_mfma_f32_16x16x32_bf16 v[124:127], v[192:195], v[216:219], v[124:127]
	v_mfma_f32_16x16x32_bf16 v[112:115], v[168:171], v[224:227], v[112:115]
	v_mfma_f32_16x16x32_bf16 v[108:111], v[192:195], v[224:227], v[108:111]
	v_mfma_f32_16x16x32_bf16 v[96:99], v[168:171], v[232:235], v[96:99]
	v_mfma_f32_16x16x32_bf16 v[92:95], v[192:195], v[232:235], v[92:95]
	v_mfma_f32_16x16x32_bf16 v[80:83], v[168:171], v[240:243], v[80:83]
	v_mfma_f32_16x16x32_bf16 v[76:79], v[192:195], v[240:243], v[76:79]
	v_mfma_f32_16x16x32_bf16 v[120:123], v[196:199], v[212:215], v[120:123]
	v_mfma_f32_16x16x32_bf16 v[116:119], v[204:207], v[212:215], v[116:119]
	v_mfma_f32_16x16x32_bf16 v[104:107], v[196:199], v[220:223], v[104:107]
	v_mfma_f32_16x16x32_bf16 v[100:103], v[204:207], v[220:223], v[100:103]
	v_mfma_f32_16x16x32_bf16 v[88:91], v[196:199], v[228:231], v[88:91]
	v_mfma_f32_16x16x32_bf16 v[84:87], v[204:207], v[228:231], v[84:87]
	v_mfma_f32_16x16x32_bf16 v[72:75], v[196:199], v[236:239], v[72:75]
	v_mfma_f32_16x16x32_bf16 v[68:71], v[204:207], v[236:239], v[68:71]
	v_mfma_f32_16x16x32_bf16 v[120:123], v[200:203], v[216:219], v[120:123]
	v_mfma_f32_16x16x32_bf16 v[116:119], v[208:211], v[216:219], v[116:119]
	v_mfma_f32_16x16x32_bf16 v[104:107], v[200:203], v[224:227], v[104:107]
	v_mfma_f32_16x16x32_bf16 v[100:103], v[208:211], v[224:227], v[100:103]
	v_mfma_f32_16x16x32_bf16 v[88:91], v[200:203], v[232:235], v[88:91]
	v_mfma_f32_16x16x32_bf16 v[84:87], v[208:211], v[232:235], v[84:87]
	v_mfma_f32_16x16x32_bf16 v[72:75], v[200:203], v[240:243], v[72:75]
	v_mfma_f32_16x16x32_bf16 v[68:71], v[208:211], v[240:243], v[68:71]
	s_barrier
	s_add_u32 s42, s48, 0x80
	s_addc_u32 s43, s49, 0
	s_add_i32 m0, s69, 0x18000
	s_add_u32 s46, s48, s53
	s_addc_u32 s47, s49, 0
	global_load_lds_dwordx4 v140, s[42:43]
	s_add_i32 m0, s69, 0x1a000
	ds_read_b128 v[212:215], v160 offset:49152
	global_load_lds_dwordx4 v144, s[42:43]
	s_add_i32 m0, s69, 0x1c000
	ds_read_b128 v[216:219], v160 offset:50176
	global_load_lds_dwordx4 v140, s[46:47]
	s_add_i32 m0, s69, 0x1e000
	ds_read_b128 v[220:223], v160 offset:51200
	global_load_lds_dwordx4 v144, s[46:47]
	ds_read_b128 v[224:227], v160 offset:52224
	ds_read_b128 v[228:231], v160 offset:53248
	ds_read_b128 v[232:235], v160 offset:54272
	ds_read_b128 v[236:239], v160 offset:55296
	ds_read_b128 v[240:243], v160 offset:56320
	s_waitcnt vmcnt(6)
	s_waitcnt lgkmcnt(0)
	s_barrier
	s_waitcnt lgkmcnt(0)
	v_mfma_f32_16x16x32_bf16 v[64:67], v[164:167], v[212:215], v[64:67]
	v_mfma_f32_16x16x32_bf16 v[60:63], v[188:191], v[212:215], v[60:63]
	v_mfma_f32_16x16x32_bf16 v[48:51], v[164:167], v[220:223], v[48:51]
	v_mfma_f32_16x16x32_bf16 v[44:47], v[188:191], v[220:223], v[44:47]
	v_mfma_f32_16x16x32_bf16 v[32:35], v[164:167], v[228:231], v[32:35]
	v_mfma_f32_16x16x32_bf16 v[28:31], v[188:191], v[228:231], v[28:31]
	v_mfma_f32_16x16x32_bf16 v[16:19], v[164:167], v[236:239], v[16:19]
	v_mfma_f32_16x16x32_bf16 v[12:15], v[188:191], v[236:239], v[12:15]
	v_mfma_f32_16x16x32_bf16 v[64:67], v[168:171], v[216:219], v[64:67]
	v_mfma_f32_16x16x32_bf16 v[60:63], v[192:195], v[216:219], v[60:63]
	v_mfma_f32_16x16x32_bf16 v[48:51], v[168:171], v[224:227], v[48:51]
	v_mfma_f32_16x16x32_bf16 v[44:47], v[192:195], v[224:227], v[44:47]
	v_mfma_f32_16x16x32_bf16 v[32:35], v[168:171], v[232:235], v[32:35]
	v_mfma_f32_16x16x32_bf16 v[28:31], v[192:195], v[232:235], v[28:31]
	v_mfma_f32_16x16x32_bf16 v[16:19], v[168:171], v[240:243], v[16:19]
	v_mfma_f32_16x16x32_bf16 v[12:15], v[192:195], v[240:243], v[12:15]
	v_mfma_f32_16x16x32_bf16 v[56:59], v[196:199], v[212:215], v[56:59]
	v_mfma_f32_16x16x32_bf16 v[52:55], v[204:207], v[212:215], v[52:55]
	v_mfma_f32_16x16x32_bf16 v[40:43], v[196:199], v[220:223], v[40:43]
	v_mfma_f32_16x16x32_bf16 v[36:39], v[204:207], v[220:223], v[36:39]
	v_mfma_f32_16x16x32_bf16 v[24:27], v[196:199], v[228:231], v[24:27]
	v_mfma_f32_16x16x32_bf16 v[20:23], v[204:207], v[228:231], v[20:23]
	v_mfma_f32_16x16x32_bf16 v[8:11], v[196:199], v[236:239], v[8:11]
	v_mfma_f32_16x16x32_bf16 v[4:7], v[204:207], v[236:239], v[4:7]
	v_mfma_f32_16x16x32_bf16 v[56:59], v[200:203], v[216:219], v[56:59]
	v_mfma_f32_16x16x32_bf16 v[52:55], v[208:211], v[216:219], v[52:55]
	v_mfma_f32_16x16x32_bf16 v[40:43], v[200:203], v[224:227], v[40:43]
	v_mfma_f32_16x16x32_bf16 v[36:39], v[208:211], v[224:227], v[36:39]
	v_mfma_f32_16x16x32_bf16 v[24:27], v[200:203], v[232:235], v[24:27]
	v_mfma_f32_16x16x32_bf16 v[20:23], v[208:211], v[232:235], v[20:23]
	v_mfma_f32_16x16x32_bf16 v[8:11], v[200:203], v[240:243], v[8:11]
	v_mfma_f32_16x16x32_bf16 v[4:7], v[208:211], v[240:243], v[4:7]
	s_barrier
	s_add_i32 s63, s63, 2
	s_add_u32 s28, s28, 0x100
	s_addc_u32 s29, s29, 0
	s_cmp_gt_u32 s63, s55
	s_mov_b64 s[42:43], s[44:45]

.Lg1_loop:
	s_add_u32 s44, s42, 0x100
	s_addc_u32 s45, s43, 0
	s_cmp_eq_u32 s63, s54
	s_cselect_b32 s50, s26, s44
	s_cselect_b32 s51, s5, s45
	s_cselect_b32 s48, s27, s28
	s_cselect_b32 s49, s23, s29
	s_add_u32 s46, s42, 0x80
	s_addc_u32 s47, s43, 0
	s_mov_b32 m0, s60
	s_add_u32 s42, s42, s53
	s_addc_u32 s43, s43, 0
	global_load_lds_dwordx4 v0, s[46:47]
	s_mov_b32 m0, s61
	ds_read_b128 v[164:167], v244
	global_load_lds_dwordx4 v142, s[46:47]
	ds_read_b128 v[168:171], v244 offset:1024
	ds_read_b128 v[188:191], v244 offset:2048
	ds_read_b128 v[192:195], v244 offset:3072
	ds_read_b128 v[196:199], v244 offset:16384
	ds_read_b128 v[200:203], v244 offset:17408
	ds_read_b128 v[204:207], v244 offset:18432
	ds_read_b128 v[208:211], v244 offset:19456
	s_add_i32 m0, s56, 0xc000
	ds_read_b128 v[212:215], v160
	global_load_lds_dwordx4 v0, s[42:43]
	s_add_i32 m0, s56, 0xe000
	ds_read_b128 v[216:219], v160 offset:1024
	global_load_lds_dwordx4 v142, s[42:43]
	ds_read_b128 v[220:223], v160 offset:2048
	ds_read_b128 v[224:227], v160 offset:3072
	ds_read_b128 v[228:231], v160 offset:4096
	ds_read_b128 v[232:235], v160 offset:5120
	ds_read_b128 v[236:239], v160 offset:6144
	ds_read_b128 v[240:243], v160 offset:7168
	s_waitcnt vmcnt(8)
	s_waitcnt lgkmcnt(8)
	s_barrier
	s_waitcnt lgkmcnt(0)
	v_mfma_f32_16x16x32_bf16 v[128:131], v[164:167], v[212:215], v[128:131]
	v_mfma_f32_16x16x32_bf16 v[124:127], v[188:191], v[212:215], v[124:127]
	v_mfma_f32_16x16x32_bf16 v[112:115], v[164:167], v[220:223], v[112:115]
	v_mfma_f32_16x16x32_bf16 v[108:111], v[188:191], v[220:223], v[108:111]
	v_mfma_f32_16x16x32_bf16 v[96:99], v[164:167], v[228:231], v[96:99]
	v_mfma_f32_16x16x32_bf16 v[92:95], v[188:191], v[228:231], v[92:95]
	v_mfma_f32_16x16x32_bf16 v[80:83], v[164:167], v[236:239], v[80:83]
	v_mfma_f32_16x16x32_bf16 v[76:79], v[188:191], v[236:239], v[76:79]
	v_mfma_f32_16x16x32_bf16 v[128:131], v[168:171], v[216:219], v[128:131]
	v_mfma_f32_16x16x32_bf16 v[124:127], v[192:195], v[216:219], v[124:127]
	v_mfma_f32_16x16x32_bf16 v[112:115], v[168:171], v[224:227], v[112:115]
	v_mfma_f32_16x16x32_bf16 v[108:111], v[192:195], v[224:227], v[108:111]
	v_mfma_f32_16x16x32_bf16 v[96:99], v[168:171], v[232:235], v[96:99]
	v_mfma_f32_16x16x32_bf16 v[92:95], v[192:195], v[232:235], v[92:95]
	v_mfma_f32_16x16x32_bf16 v[80:83], v[168:171], v[240:243], v[80:83]
	v_mfma_f32_16x16x32_bf16 v[76:79], v[192:195], v[240:243], v[76:79]
	v_mfma_f32_16x16x32_bf16 v[120:123], v[196:199], v[212:215], v[120:123]
	v_mfma_f32_16x16x32_bf16 v[116:119], v[204:207], v[212:215], v[116:119]
	v_mfma_f32_16x16x32_bf16 v[104:107], v[196:199], v[220:223], v[104:107]
	v_mfma_f32_16x16x32_bf16 v[100:103], v[204:207], v[220:223], v[100:103]
	v_mfma_f32_16x16x32_bf16 v[88:91], v[196:199], v[228:231], v[88:91]
	v_mfma_f32_16x16x32_bf16 v[84:87], v[204:207], v[228:231], v[84:87]
	v_mfma_f32_16x16x32_bf16 v[72:75], v[196:199], v[236:239], v[72:75]
	v_mfma_f32_16x16x32_bf16 v[68:71], v[204:207], v[236:239], v[68:71]
	v_mfma_f32_16x16x32_bf16 v[120:123], v[200:203], v[216:219], v[120:123]
	v_mfma_f32_16x16x32_bf16 v[116:119], v[208:211], v[216:219], v[116:119]
	v_mfma_f32_16x16x32_bf16 v[104:107], v[200:203], v[224:227], v[104:107]
	v_mfma_f32_16x16x32_bf16 v[100:103], v[208:211], v[224:227], v[100:103]
	v_mfma_f32_16x16x32_bf16 v[88:91], v[200:203], v[232:235], v[88:91]
	v_mfma_f32_16x16x32_bf16 v[84:87], v[208:211], v[232:235], v[84:87]
	v_mfma_f32_16x16x32_bf16 v[72:75], v[200:203], v[240:243], v[72:75]
	v_mfma_f32_16x16x32_bf16 v[68:71], v[208:211], v[240:243], v[68:71]
	s_barrier
	s_add_i32 m0, s69, 0x10000
	s_add_u32 s42, s48, s90
	s_addc_u32 s43, s49, 0
	global_load_lds_dwordx4 v140, s[48:49]
	s_add_i32 m0, s69, 0x12000
	ds_read_b128 v[212:215], v160 offset:16384
	global_load_lds_dwordx4 v144, s[48:49]
	s_add_i32 m0, s69, 0x14000
	ds_read_b128 v[216:219], v160 offset:17408
	global_load_lds_dwordx4 v140, s[42:43]
	s_add_i32 m0, s69, 0x16000
	ds_read_b128 v[220:223], v160 offset:18432
	global_load_lds_dwordx4 v144, s[42:43]
	ds_read_b128 v[224:227], v160 offset:19456
	ds_read_b128 v[228:231], v160 offset:20480
	ds_read_b128 v[232:235], v160 offset:21504
	ds_read_b128 v[236:239], v160 offset:22528
	ds_read_b128 v[240:243], v160 offset:23552
	s_waitcnt vmcnt(6)
	s_waitcnt lgkmcnt(0)
	s_barrier
	s_waitcnt lgkmcnt(0)
	v_mfma_f32_16x16x32_bf16 v[64:67], v[164:167], v[212:215], v[64:67]
	v_mfma_f32_16x16x32_bf16 v[60:63], v[188:191], v[212:215], v[60:63]
	v_mfma_f32_16x16x32_bf16 v[48:51], v[164:167], v[220:223], v[48:51]
	v_mfma_f32_16x16x32_bf16 v[44:47], v[188:191], v[220:223], v[44:47]
	v_mfma_f32_16x16x32_bf16 v[32:35], v[164:167], v[228:231], v[32:35]
	v_mfma_f32_16x16x32_bf16 v[28:31], v[188:191], v[228:231], v[28:31]
	v_mfma_f32_16x16x32_bf16 v[16:19], v[164:167], v[236:239], v[16:19]
	v_mfma_f32_16x16x32_bf16 v[12:15], v[188:191], v[236:239], v[12:15]
	v_mfma_f32_16x16x32_bf16 v[64:67], v[168:171], v[216:219], v[64:67]
	v_mfma_f32_16x16x32_bf16 v[60:63], v[192:195], v[216:219], v[60:63]
	v_mfma_f32_16x16x32_bf16 v[48:51], v[168:171], v[224:227], v[48:51]
	v_mfma_f32_16x16x32_bf16 v[44:47], v[192:195], v[224:227], v[44:47]
	v_mfma_f32_16x16x32_bf16 v[32:35], v[168:171], v[232:235], v[32:35]
	v_mfma_f32_16x16x32_bf16 v[28:31], v[192:195], v[232:235], v[28:31]
	v_mfma_f32_16x16x32_bf16 v[16:19], v[168:171], v[240:243], v[16:19]
	v_mfma_f32_16x16x32_bf16 v[12:15], v[192:195], v[240:243], v[12:15]
	v_mfma_f32_16x16x32_bf16 v[56:59], v[196:199], v[212:215], v[56:59]
	v_mfma_f32_16x16x32_bf16 v[52:55], v[204:207], v[212:215], v[52:55]
	v_mfma_f32_16x16x32_bf16 v[40:43], v[196:199], v[220:223], v[40:43]
	v_mfma_f32_16x16x32_bf16 v[36:39], v[204:207], v[220:223], v[36:39]
	v_mfma_f32_16x16x32_bf16 v[24:27], v[196:199], v[228:231], v[24:27]
	v_mfma_f32_16x16x32_bf16 v[20:23], v[204:207], v[228:231], v[20:23]
	v_mfma_f32_16x16x32_bf16 v[8:11], v[196:199], v[236:239], v[8:11]
	v_mfma_f32_16x16x32_bf16 v[4:7], v[204:207], v[236:239], v[4:7]
	v_mfma_f32_16x16x32_bf16 v[56:59], v[200:203], v[216:219], v[56:59]
	v_mfma_f32_16x16x32_bf16 v[52:55], v[208:211], v[216:219], v[52:55]
	v_mfma_f32_16x16x32_bf16 v[40:43], v[200:203], v[224:227], v[40:43]
	v_mfma_f32_16x16x32_bf16 v[36:39], v[208:211], v[224:227], v[36:39]
	v_mfma_f32_16x16x32_bf16 v[24:27], v[200:203], v[232:235], v[24:27]
	v_mfma_f32_16x16x32_bf16 v[20:23], v[208:211], v[232:235], v[20:23]
	v_mfma_f32_16x16x32_bf16 v[8:11], v[200:203], v[240:243], v[8:11]
	v_mfma_f32_16x16x32_bf16 v[4:7], v[208:211], v[240:243], v[4:7]
	s_barrier
	s_mov_b32 m0, s56
	s_add_u32 s42, s50, s90
	s_addc_u32 s43, s51, 0
	global_load_lds_dwordx4 v0, s[50:51]
	s_mov_b32 m0, s57
	ds_read_b128 v[164:167], v244 offset:32768
	global_load_lds_dwordx4 v142, s[50:51]
	ds_read_b128 v[168:171], v244 offset:33792
	ds_read_b128 v[188:191], v244 offset:34816
	ds_read_b128 v[192:195], v244 offset:35840
	ds_read_b128 v[196:199], v244 offset:49152
	ds_read_b128 v[200:203], v244 offset:50176
	ds_read_b128 v[204:207], v244 offset:51200
	ds_read_b128 v[208:211], v244 offset:52224
	s_mov_b32 m0, s58
	ds_read_b128 v[212:215], v160 offset:32768
	global_load_lds_dwordx4 v0, s[42:43]
	s_mov_b32 m0, s59
	ds_read_b128 v[216:219], v160 offset:33792
	global_load_lds_dwordx4 v142, s[42:43]
	ds_read_b128 v[220:223], v160 offset:34816
	ds_read_b128 v[224:227], v160 offset:35840
	ds_read_b128 v[228:231], v160 offset:36864
	ds_read_b128 v[232:235], v160 offset:37888
	ds_read_b128 v[236:239], v160 offset:38912
	ds_read_b128 v[240:243], v160 offset:39936
	s_waitcnt vmcnt(8)
	s_waitcnt lgkmcnt(8)
	s_barrier
	s_waitcnt lgkmcnt(0)
	v_mfma_f32_16x16x32_bf16 v[128:131], v[164:167], v[212:215], v[128:131]
	v_mfma_f32_16x16x32_bf16 v[124:127], v[188:191], v[212:215], v[124:127]
	v_mfma_f32_16x16x32_bf16 v[112:115], v[164:167], v[220:223], v[112:115]
	v_mfma_f32_16x16x32_bf16 v[108:111], v[188:191], v[220:223], v[108:111]
	v_mfma_f32_16x16x32_bf16 v[96:99], v[164:167], v[228:231], v[96:99]
	v_mfma_f32_16x16x32_bf16 v[92:95], v[188:191], v[228:231], v[92:95]
	v_mfma_f32_16x16x32_bf16 v[80:83], v[164:167], v[236:239], v[80:83]
	v_mfma_f32_16x16x32_bf16 v[76:79], v[188:191], v[236:239], v[76:79]
	v_mfma_f32_16x16x32_bf16 v[128:131], v[168:171], v[216:219], v[128:131]
	v_mfma_f32_16x16x32_bf16 v[124:127], v[192:195], v[216:219], v[124:127]
	v_mfma_f32_16x16x32_bf16 v[112:115], v[168:171], v[224:227], v[112:115]
	v_mfma_f32_16x16x32_bf16 v[108:111], v[192:195], v[224:227], v[108:111]
	v_mfma_f32_16x16x32_bf16 v[96:99], v[168:171], v[232:235], v[96:99]
	v_mfma_f32_16x16x32_bf16 v[92:95], v[192:195], v[232:235], v[92:95]
	v_mfma_f32_16x16x32_bf16 v[80:83], v[168:171], v[240:243], v[80:83]
	v_mfma_f32_16x16x32_bf16 v[76:79], v[192:195], v[240:243], v[76:79]
	v_mfma_f32_16x16x32_bf16 v[120:123], v[196:199], v[212:215], v[120:123]
	v_mfma_f32_16x16x32_bf16 v[116:119], v[204:207], v[212:215], v[116:119]
	v_mfma_f32_16x16x32_bf16 v[104:107], v[196:199], v[220:223], v[104:107]
	v_mfma_f32_16x16x32_bf16 v[100:103], v[204:207], v[220:223], v[100:103]
	v_mfma_f32_16x16x32_bf16 v[88:91], v[196:199], v[228:231], v[88:91]
	v_mfma_f32_16x16x32_bf16 v[84:87], v[204:207], v[228:231], v[84:87]
	v_mfma_f32_16x16x32_bf16 v[72:75], v[196:199], v[236:239], v[72:75]
	v_mfma_f32_16x16x32_bf16 v[68:71], v[204:207], v[236:239], v[68:71]
	v_mfma_f32_16x16x32_bf16 v[120:123], v[200:203], v[216:219], v[120:123]
	v_mfma_f32_16x16x32_bf16 v[116:119], v[208:211], v[216:219], v[116:119]
	v_mfma_f32_16x16x32_bf16 v[104:107], v[200:203], v[224:227], v[104:107]
	v_mfma_f32_16x16x32_bf16 v[100:103], v[208:211], v[224:227], v[100:103]
	v_mfma_f32_16x16x32_bf16 v[88:91], v[200:203], v[232:235], v[88:91]
	v_mfma_f32_16x16x32_bf16 v[84:87], v[208:211], v[232:235], v[84:87]
	v_mfma_f32_16x16x32_bf16 v[72:75], v[200:203], v[240:243], v[72:75]
	v_mfma_f32_16x16x32_bf16 v[68:71], v[208:211], v[240:243], v[68:71]
	s_barrier
	s_add_u32 s42, s48, 0x80
	s_addc_u32 s43, s49, 0
	s_add_i32 m0, s69, 0x18000
	s_add_u32 s46, s48, s53
	s_addc_u32 s47, s49, 0
	global_load_lds_dwordx4 v140, s[42:43]
	s_add_i32 m0, s69, 0x1a000
	ds_read_b128 v[212:215], v160 offset:49152
	global_load_lds_dwordx4 v144, s[42:43]
	s_add_i32 m0, s69, 0x1c000
	ds_read_b128 v[216:219], v160 offset:50176
	global_load_lds_dwordx4 v140, s[46:47]
	s_add_i32 m0, s69, 0x1e000
	ds_read_b128 v[220:223], v160 offset:51200
	global_load_lds_dwordx4 v144, s[46:47]
	ds_read_b128 v[224:227], v160 offset:52224
	ds_read_b128 v[228:231], v160 offset:53248
	ds_read_b128 v[232:235], v160 offset:54272
	ds_read_b128 v[236:239], v160 offset:55296
	ds_read_b128 v[240:243], v160 offset:56320
	s_waitcnt vmcnt(6)
	s_waitcnt lgkmcnt(0)
	s_barrier
	s_waitcnt lgkmcnt(0)
	v_mfma_f32_16x16x32_bf16 v[64:67], v[164:167], v[212:215], v[64:67]
	v_mfma_f32_16x16x32_bf16 v[60:63], v[188:191], v[212:215], v[60:63]
	v_mfma_f32_16x16x32_bf16 v[48:51], v[164:167], v[220:223], v[48:51]
	v_mfma_f32_16x16x32_bf16 v[44:47], v[188:191], v[220:223], v[44:47]
	v_mfma_f32_16x16x32_bf16 v[32:35], v[164:167], v[228:231], v[32:35]
	v_mfma_f32_16x16x32_bf16 v[28:31], v[188:191], v[228:231], v[28:31]
	v_mfma_f32_16x16x32_bf16 v[16:19], v[164:167], v[236:239], v[16:19]
	v_mfma_f32_16x16x32_bf16 v[12:15], v[188:191], v[236:239], v[12:15]
	v_mfma_f32_16x16x32_bf16 v[64:67], v[168:171], v[216:219], v[64:67]
	v_mfma_f32_16x16x32_bf16 v[60:63], v[192:195], v[216:219], v[60:63]
	v_mfma_f32_16x16x32_bf16 v[48:51], v[168:171], v[224:227], v[48:51]
	v_mfma_f32_16x16x32_bf16 v[44:47], v[192:195], v[224:227], v[44:47]
	v_mfma_f32_16x16x32_bf16 v[32:35], v[168:171], v[232:235], v[32:35]
	v_mfma_f32_16x16x32_bf16 v[28:31], v[192:195], v[232:235], v[28:31]
	v_mfma_f32_16x16x32_bf16 v[16:19], v[168:171], v[240:243], v[16:19]
	v_mfma_f32_16x16x32_bf16 v[12:15], v[192:195], v[240:243], v[12:15]
	v_mfma_f32_16x16x32_bf16 v[56:59], v[196:199], v[212:215], v[56:59]
	v_mfma_f32_16x16x32_bf16 v[52:55], v[204:207], v[212:215], v[52:55]
	v_mfma_f32_16x16x32_bf16 v[40:43], v[196:199], v[220:223], v[40:43]
	v_mfma_f32_16x16x32_bf16 v[36:39], v[204:207], v[220:223], v[36:39]
	v_mfma_f32_16x16x32_bf16 v[24:27], v[196:199], v[228:231], v[24:27]
	v_mfma_f32_16x16x32_bf16 v[20:23], v[204:207], v[228:231], v[20:23]
	v_mfma_f32_16x16x32_bf16 v[8:11], v[196:199], v[236:239], v[8:11]
	v_mfma_f32_16x16x32_bf16 v[4:7], v[204:207], v[236:239], v[4:7]
	v_mfma_f32_16x16x32_bf16 v[56:59], v[200:203], v[216:219], v[56:59]
	v_mfma_f32_16x16x32_bf16 v[52:55], v[208:211], v[216:219], v[52:55]
	v_mfma_f32_16x16x32_bf16 v[40:43], v[200:203], v[224:227], v[40:43]
	v_mfma_f32_16x16x32_bf16 v[36:39], v[208:211], v[224:227], v[36:39]
	v_mfma_f32_16x16x32_bf16 v[24:27], v[200:203], v[232:235], v[24:27]
	v_mfma_f32_16x16x32_bf16 v[20:23], v[208:211], v[232:235], v[20:23]
	v_mfma_f32_16x16x32_bf16 v[8:11], v[200:203], v[240:243], v[8:11]
	v_mfma_f32_16x16x32_bf16 v[4:7], v[208:211], v[240:243], v[4:7]
	s_barrier
	s_add_i32 s63, s63, 2
	s_add_u32 s28, s28, 0x100
	s_addc_u32 s29, s29, 0
	s_cmp_gt_u32 s63, s55
	s_mov_b64 s[42:43], s[44:45]
	s_cbranch_scc0 .Lg1_loop
	v_readlane_b32 s5, v250, 0
	v_readlane_b32 s23, v250, 1
	v_readlane_b32 s26, v250, 2
	v_readlane_b32 s27, v250, 3
	v_readlane_b32 s28, v250, 4
	v_readlane_b32 s29, v250, 5
	v_readlane_b32 s42, v250, 6
	v_readlane_b32 s43, v250, 7
	v_readlane_b32 s44, v250, 8
	v_readlane_b32 s45, v250, 9
	v_readlane_b32 s46, v250, 10
	v_readlane_b32 s47, v250, 11
	v_readlane_b32 s48, v250, 12
	v_readlane_b32 s49, v250, 13
	v_readlane_b32 s50, v250, 14
	v_readlane_b32 s51, v250, 15
	v_readlane_b32 s53, v250, 16
	v_readlane_b32 s54, v250, 17
	v_readlane_b32 s55, v250, 18
	v_readlane_b32 s56, v250, 19
	v_readlane_b32 s57, v250, 20
	v_readlane_b32 s58, v250, 21
	v_readlane_b32 s59, v250, 22
	v_readlane_b32 s60, v250, 23
	v_readlane_b32 s61, v250, 24
	v_readlane_b32 s63, v250, 25
	v_readlane_b32 s64, v250, 26
	v_readlane_b32 s65, v250, 27
	s_and_b64 vcc, exec, s[14:15]
	s_cbranch_vccz .LBB0_419
	s_barrier
.LBB0_419:
	s_setprio 0
	v_lshlrev_b32_e32 v132, 8, v132
	v_mov_b32_e32 v154, v174
	v_add_u32_e32 v132, s70, v132
	v_cndmask_b32_e64 v152, 0, 1, s[46:47]
	v_and_or_b32 v150, v154, 15, v132
	v_ashrrev_i32_e32 v151, 31, v150
	v_mov_b32_e32 v132, 1.0
	v_cmp_ne_u32_e64 s[42:43], 1, v152
	s_andn2_b64 vcc, exec, s[46:47]
	v_lshl_add_u64 v[152:153], v[150:151], 2, s[36:37]
	v_mov_b32_e32 v156, 1.0
	s_cbranch_vccnz .LBB0_421
	global_load_dword v156, v[152:153], off

.Lprio_skip:
	v_add_u32_e32 v240, 0x10000, v3
	s_ashr_i32 s5, s4, 31
	s_lshl_b64 s[24:25], s[4:5], 19
	s_add_u32 s24, s52, s24
	s_addc_u32 s25, s53, s25
	s_and_b64 s[26:27], s[40:41], exec
	s_cselect_b32 s5, s25, s43
	s_cselect_b32 s26, s24, s42
	s_ashr_i32 s23, s22, 31
	s_lshl_b64 s[28:29], s[22:23], 19
	s_add_u32 s36, s54, s28
	s_addc_u32 s37, s55, s29
	s_and_b64 s[28:29], s[40:41], exec
	s_cselect_b32 s23, s37, s45
	s_cselect_b32 s27, s36, s44
	s_add_u32 s28, s44, 0x100
	v_mov_b32_e32 v4, 0
	s_addc_u32 s29, s45, 0
	s_mov_b32 s63, -2
	s_add_u32 s44, s42, 0x100
	s_addc_u32 s45, s43, 0
	s_cmp_eq_u32 s63, 12
	s_cselect_b32 s50, s26, s44
	s_cselect_b32 s51, s5, s45
	s_cselect_b32 s48, s27, s28
	s_cselect_b32 s49, s23, s29
	s_add_u32 s46, s42, 0x80
	s_addc_u32 s47, s43, 0
	s_mov_b32 m0, s60
	s_add_u32 s42, s42, 0x40080
	s_addc_u32 s43, s43, 0
	global_load_lds_dwordx4 v144, s[46:47]
	s_mov_b32 m0, s61
	ds_read_b128 v[146:149], v240
	global_load_lds_dwordx4 v140, s[46:47]
	ds_read_b128 v[150:153], v240 offset:1024
	ds_read_b128 v[154:157], v240 offset:2048
	ds_read_b128 v[158:161], v240 offset:3072
	ds_read_b128 v[162:165], v240 offset:16384
	ds_read_b128 v[166:169], v240 offset:17408
	ds_read_b128 v[170:173], v240 offset:18432
	ds_read_b128 v[186:189], v240 offset:19456
	s_add_i32 m0, s56, 0xc000
	ds_read_b128 v[190:193], v132
	global_load_lds_dwordx4 v144, s[42:43]
	s_add_i32 m0, s56, 0xe000
	ds_read_b128 v[194:197], v132 offset:1024
	global_load_lds_dwordx4 v140, s[42:43]
	ds_read_b128 v[198:201], v132 offset:2048
	ds_read_b128 v[202:205], v132 offset:3072
	ds_read_b128 v[206:209], v132 offset:4096
	ds_read_b128 v[210:213], v132 offset:5120
	ds_read_b128 v[214:217], v132 offset:6144
	ds_read_b128 v[218:221], v132 offset:7168
	s_waitcnt vmcnt(8)
	s_waitcnt lgkmcnt(8)
	s_barrier
	s_waitcnt lgkmcnt(0)
	v_mfma_f32_16x16x32_bf16 v[128:131], v[146:149], v[190:193], 0
	v_mfma_f32_16x16x32_bf16 v[124:127], v[154:157], v[190:193], 0
	v_mfma_f32_16x16x32_bf16 v[112:115], v[146:149], v[198:201], 0
	v_mfma_f32_16x16x32_bf16 v[108:111], v[154:157], v[198:201], 0
	v_mfma_f32_16x16x32_bf16 v[96:99], v[146:149], v[206:209], 0
	v_mfma_f32_16x16x32_bf16 v[92:95], v[154:157], v[206:209], 0
	v_mfma_f32_16x16x32_bf16 v[80:83], v[146:149], v[214:217], 0
	v_mfma_f32_16x16x32_bf16 v[76:79], v[154:157], v[214:217], 0
	v_mfma_f32_16x16x32_bf16 v[128:131], v[150:153], v[194:197], v[128:131]
	v_mfma_f32_16x16x32_bf16 v[124:127], v[158:161], v[194:197], v[124:127]
	v_mfma_f32_16x16x32_bf16 v[112:115], v[150:153], v[202:205], v[112:115]
	v_mfma_f32_16x16x32_bf16 v[108:111], v[158:161], v[202:205], v[108:111]
	v_mfma_f32_16x16x32_bf16 v[96:99], v[150:153], v[210:213], v[96:99]
	v_mfma_f32_16x16x32_bf16 v[92:95], v[158:161], v[210:213], v[92:95]
	v_mfma_f32_16x16x32_bf16 v[80:83], v[150:153], v[218:221], v[80:83]
	v_mfma_f32_16x16x32_bf16 v[76:79], v[158:161], v[218:221], v[76:79]
	v_mfma_f32_16x16x32_bf16 v[120:123], v[162:165], v[190:193], 0
	v_mfma_f32_16x16x32_bf16 v[116:119], v[170:173], v[190:193], 0
	v_mfma_f32_16x16x32_bf16 v[104:107], v[162:165], v[198:201], 0
	v_mfma_f32_16x16x32_bf16 v[100:103], v[170:173], v[198:201], 0
	v_mfma_f32_16x16x32_bf16 v[88:91], v[162:165], v[206:209], 0
	v_mfma_f32_16x16x32_bf16 v[84:87], v[170:173], v[206:209], 0
	v_mfma_f32_16x16x32_bf16 v[72:75], v[162:165], v[214:217], 0
	v_mfma_f32_16x16x32_bf16 v[68:71], v[170:173], v[214:217], 0
	v_mfma_f32_16x16x32_bf16 v[120:123], v[166:169], v[194:197], v[120:123]
	v_mfma_f32_16x16x32_bf16 v[116:119], v[186:189], v[194:197], v[116:119]
	v_mfma_f32_16x16x32_bf16 v[104:107], v[166:169], v[202:205], v[104:107]
	v_mfma_f32_16x16x32_bf16 v[100:103], v[186:189], v[202:205], v[100:103]
	v_mfma_f32_16x16x32_bf16 v[88:91], v[166:169], v[210:213], v[88:91]
	v_mfma_f32_16x16x32_bf16 v[84:87], v[186:189], v[210:213], v[84:87]
	v_mfma_f32_16x16x32_bf16 v[72:75], v[166:169], v[218:221], v[72:75]
	v_mfma_f32_16x16x32_bf16 v[68:71], v[186:189], v[218:221], v[68:71]
	s_barrier
	s_add_i32 m0, s69, 0x10000
	s_add_u32 s42, s48, 0x40000
	s_addc_u32 s43, s49, 0
	global_load_lds_dwordx4 v142, s[48:49]
	s_add_i32 m0, s69, 0x12000
	ds_read_b128 v[190:193], v132 offset:16384
	global_load_lds_dwordx4 v0, s[48:49]
	s_add_i32 m0, s69, 0x14000
	ds_read_b128 v[194:197], v132 offset:17408
	global_load_lds_dwordx4 v142, s[42:43]
	s_add_i32 m0, s69, 0x16000
	ds_read_b128 v[198:201], v132 offset:18432
	global_load_lds_dwordx4 v0, s[42:43]
	ds_read_b128 v[202:205], v132 offset:19456
	ds_read_b128 v[206:209], v132 offset:20480
	ds_read_b128 v[210:213], v132 offset:21504
	ds_read_b128 v[214:217], v132 offset:22528
	ds_read_b128 v[218:221], v132 offset:23552
	s_waitcnt vmcnt(6)
	s_waitcnt lgkmcnt(0)
	s_barrier
	s_waitcnt lgkmcnt(0)
	v_mfma_f32_16x16x32_bf16 v[64:67], v[146:149], v[190:193], 0
	v_mfma_f32_16x16x32_bf16 v[60:63], v[154:157], v[190:193], 0
	v_mfma_f32_16x16x32_bf16 v[48:51], v[146:149], v[198:201], 0
	v_mfma_f32_16x16x32_bf16 v[44:47], v[154:157], v[198:201], 0
	v_mfma_f32_16x16x32_bf16 v[32:35], v[146:149], v[206:209], 0
	v_mfma_f32_16x16x32_bf16 v[28:31], v[154:157], v[206:209], 0
	v_mfma_f32_16x16x32_bf16 v[16:19], v[146:149], v[214:217], 0
	v_mfma_f32_16x16x32_bf16 v[12:15], v[154:157], v[214:217], 0
	v_mfma_f32_16x16x32_bf16 v[64:67], v[150:153], v[194:197], v[64:67]
	v_mfma_f32_16x16x32_bf16 v[60:63], v[158:161], v[194:197], v[60:63]
	v_mfma_f32_16x16x32_bf16 v[48:51], v[150:153], v[202:205], v[48:51]
	v_mfma_f32_16x16x32_bf16 v[44:47], v[158:161], v[202:205], v[44:47]
	v_mfma_f32_16x16x32_bf16 v[32:35], v[150:153], v[210:213], v[32:35]
	v_mfma_f32_16x16x32_bf16 v[28:31], v[158:161], v[210:213], v[28:31]
	v_mfma_f32_16x16x32_bf16 v[16:19], v[150:153], v[218:221], v[16:19]
	v_mfma_f32_16x16x32_bf16 v[12:15], v[158:161], v[218:221], v[12:15]
	v_mfma_f32_16x16x32_bf16 v[56:59], v[162:165], v[190:193], 0
	v_mfma_f32_16x16x32_bf16 v[52:55], v[170:173], v[190:193], 0
	v_mfma_f32_16x16x32_bf16 v[40:43], v[162:165], v[198:201], 0
	v_mfma_f32_16x16x32_bf16 v[36:39], v[170:173], v[198:201], 0
	v_mfma_f32_16x16x32_bf16 v[24:27], v[162:165], v[206:209], 0
	v_mfma_f32_16x16x32_bf16 v[20:23], v[170:173], v[206:209], 0
	v_mfma_f32_16x16x32_bf16 v[8:11], v[162:165], v[214:217], 0
	v_mfma_f32_16x16x32_bf16 v[4:7], v[170:173], v[214:217], 0
	v_mfma_f32_16x16x32_bf16 v[56:59], v[166:169], v[194:197], v[56:59]
	v_mfma_f32_16x16x32_bf16 v[52:55], v[186:189], v[194:197], v[52:55]
	v_mfma_f32_16x16x32_bf16 v[40:43], v[166:169], v[202:205], v[40:43]
	v_mfma_f32_16x16x32_bf16 v[36:39], v[186:189], v[202:205], v[36:39]
	v_mfma_f32_16x16x32_bf16 v[24:27], v[166:169], v[210:213], v[24:27]
	v_mfma_f32_16x16x32_bf16 v[20:23], v[186:189], v[210:213], v[20:23]
	v_mfma_f32_16x16x32_bf16 v[8:11], v[166:169], v[218:221], v[8:11]
	v_mfma_f32_16x16x32_bf16 v[4:7], v[186:189], v[218:221], v[4:7]
	s_barrier
	s_mov_b32 m0, s56
	s_add_u32 s42, s50, 0x40000
	s_addc_u32 s43, s51, 0
	global_load_lds_dwordx4 v144, s[50:51]
	s_mov_b32 m0, s57
	ds_read_b128 v[146:149], v240 offset:32768
	global_load_lds_dwordx4 v140, s[50:51]
	ds_read_b128 v[150:153], v240 offset:33792
	ds_read_b128 v[154:157], v240 offset:34816
	ds_read_b128 v[158:161], v240 offset:35840
	ds_read_b128 v[162:165], v240 offset:49152
	ds_read_b128 v[166:169], v240 offset:50176
	ds_read_b128 v[170:173], v240 offset:51200
	ds_read_b128 v[186:189], v240 offset:52224
	s_mov_b32 m0, s58
	ds_read_b128 v[190:193], v132 offset:32768
	global_load_lds_dwordx4 v144, s[42:43]
	s_mov_b32 m0, s59
	ds_read_b128 v[194:197], v132 offset:33792
	global_load_lds_dwordx4 v140, s[42:43]
	ds_read_b128 v[198:201], v132 offset:34816
	ds_read_b128 v[202:205], v132 offset:35840
	ds_read_b128 v[206:209], v132 offset:36864
	ds_read_b128 v[210:213], v132 offset:37888
	ds_read_b128 v[214:217], v132 offset:38912
	ds_read_b128 v[218:221], v132 offset:39936
	s_waitcnt vmcnt(8)
	s_waitcnt lgkmcnt(8)
	s_barrier
	s_waitcnt lgkmcnt(0)
	v_mfma_f32_16x16x32_bf16 v[128:131], v[146:149], v[190:193], v[128:131]
	v_mfma_f32_16x16x32_bf16 v[124:127], v[154:157], v[190:193], v[124:127]
	v_mfma_f32_16x16x32_bf16 v[112:115], v[146:149], v[198:201], v[112:115]
	v_mfma_f32_16x16x32_bf16 v[108:111], v[154:157], v[198:201], v[108:111]
	v_mfma_f32_16x16x32_bf16 v[96:99], v[146:149], v[206:209], v[96:99]
	v_mfma_f32_16x16x32_bf16 v[92:95], v[154:157], v[206:209], v[92:95]
	v_mfma_f32_16x16x32_bf16 v[80:83], v[146:149], v[214:217], v[80:83]
	v_mfma_f32_16x16x32_bf16 v[76:79], v[154:157], v[214:217], v[76:79]
	v_mfma_f32_16x16x32_bf16 v[128:131], v[150:153], v[194:197], v[128:131]
	v_mfma_f32_16x16x32_bf16 v[124:127], v[158:161], v[194:197], v[124:127]
	v_mfma_f32_16x16x32_bf16 v[112:115], v[150:153], v[202:205], v[112:115]
	v_mfma_f32_16x16x32_bf16 v[108:111], v[158:161], v[202:205], v[108:111]
	v_mfma_f32_16x16x32_bf16 v[96:99], v[150:153], v[210:213], v[96:99]
	v_mfma_f32_16x16x32_bf16 v[92:95], v[158:161], v[210:213], v[92:95]
	v_mfma_f32_16x16x32_bf16 v[80:83], v[150:153], v[218:221], v[80:83]
	v_mfma_f32_16x16x32_bf16 v[76:79], v[158:161], v[218:221], v[76:79]
	v_mfma_f32_16x16x32_bf16 v[120:123], v[162:165], v[190:193], v[120:123]
	v_mfma_f32_16x16x32_bf16 v[116:119], v[170:173], v[190:193], v[116:119]
	v_mfma_f32_16x16x32_bf16 v[104:107], v[162:165], v[198:201], v[104:107]
	v_mfma_f32_16x16x32_bf16 v[100:103], v[170:173], v[198:201], v[100:103]
	v_mfma_f32_16x16x32_bf16 v[88:91], v[162:165], v[206:209], v[88:91]
	v_mfma_f32_16x16x32_bf16 v[84:87], v[170:173], v[206:209], v[84:87]
	v_mfma_f32_16x16x32_bf16 v[72:75], v[162:165], v[214:217], v[72:75]
	v_mfma_f32_16x16x32_bf16 v[68:71], v[170:173], v[214:217], v[68:71]
	v_mfma_f32_16x16x32_bf16 v[120:123], v[166:169], v[194:197], v[120:123]
	v_mfma_f32_16x16x32_bf16 v[116:119], v[186:189], v[194:197], v[116:119]
	v_mfma_f32_16x16x32_bf16 v[104:107], v[166:169], v[202:205], v[104:107]
	v_mfma_f32_16x16x32_bf16 v[100:103], v[186:189], v[202:205], v[100:103]
	v_mfma_f32_16x16x32_bf16 v[88:91], v[166:169], v[210:213], v[88:91]
	v_mfma_f32_16x16x32_bf16 v[84:87], v[186:189], v[210:213], v[84:87]
	v_mfma_f32_16x16x32_bf16 v[72:75], v[166:169], v[218:221], v[72:75]
	v_mfma_f32_16x16x32_bf16 v[68:71], v[186:189], v[218:221], v[68:71]
	s_barrier
	s_add_u32 s42, s48, 0x80
	s_addc_u32 s43, s49, 0
	s_add_i32 m0, s69, 0x18000
	s_add_u32 s46, s48, 0x40080
	s_addc_u32 s47, s49, 0
	global_load_lds_dwordx4 v142, s[42:43]
	s_add_i32 m0, s69, 0x1a000
	ds_read_b128 v[190:193], v132 offset:49152
	global_load_lds_dwordx4 v0, s[42:43]
	s_add_i32 m0, s69, 0x1c000
	ds_read_b128 v[194:197], v132 offset:50176
	global_load_lds_dwordx4 v142, s[46:47]
	s_add_i32 m0, s69, 0x1e000
	ds_read_b128 v[198:201], v132 offset:51200
	global_load_lds_dwordx4 v0, s[46:47]
	ds_read_b128 v[202:205], v132 offset:52224
	ds_read_b128 v[206:209], v132 offset:53248
	ds_read_b128 v[210:213], v132 offset:54272
	ds_read_b128 v[214:217], v132 offset:55296
	ds_read_b128 v[218:221], v132 offset:56320
	s_waitcnt vmcnt(6)
	s_waitcnt lgkmcnt(0)
	s_barrier
	s_waitcnt lgkmcnt(0)
	v_mfma_f32_16x16x32_bf16 v[64:67], v[146:149], v[190:193], v[64:67]
	v_mfma_f32_16x16x32_bf16 v[60:63], v[154:157], v[190:193], v[60:63]
	v_mfma_f32_16x16x32_bf16 v[48:51], v[146:149], v[198:201], v[48:51]
	v_mfma_f32_16x16x32_bf16 v[44:47], v[154:157], v[198:201], v[44:47]
	v_mfma_f32_16x16x32_bf16 v[32:35], v[146:149], v[206:209], v[32:35]
	v_mfma_f32_16x16x32_bf16 v[28:31], v[154:157], v[206:209], v[28:31]
	v_mfma_f32_16x16x32_bf16 v[16:19], v[146:149], v[214:217], v[16:19]
	v_mfma_f32_16x16x32_bf16 v[12:15], v[154:157], v[214:217], v[12:15]
	v_mfma_f32_16x16x32_bf16 v[64:67], v[150:153], v[194:197], v[64:67]
	v_mfma_f32_16x16x32_bf16 v[60:63], v[158:161], v[194:197], v[60:63]
	v_mfma_f32_16x16x32_bf16 v[48:51], v[150:153], v[202:205], v[48:51]
	v_mfma_f32_16x16x32_bf16 v[44:47], v[158:161], v[202:205], v[44:47]
	v_mfma_f32_16x16x32_bf16 v[32:35], v[150:153], v[210:213], v[32:35]
	v_mfma_f32_16x16x32_bf16 v[28:31], v[158:161], v[210:213], v[28:31]
	v_mfma_f32_16x16x32_bf16 v[16:19], v[150:153], v[218:221], v[16:19]
	v_mfma_f32_16x16x32_bf16 v[12:15], v[158:161], v[218:221], v[12:15]
	v_mfma_f32_16x16x32_bf16 v[56:59], v[162:165], v[190:193], v[56:59]
	v_mfma_f32_16x16x32_bf16 v[52:55], v[170:173], v[190:193], v[52:55]
	v_mfma_f32_16x16x32_bf16 v[40:43], v[162:165], v[198:201], v[40:43]
	v_mfma_f32_16x16x32_bf16 v[36:39], v[170:173], v[198:201], v[36:39]
	v_mfma_f32_16x16x32_bf16 v[24:27], v[162:165], v[206:209], v[24:27]
	v_mfma_f32_16x16x32_bf16 v[20:23], v[170:173], v[206:209], v[20:23]
	v_mfma_f32_16x16x32_bf16 v[8:11], v[162:165], v[214:217], v[8:11]
	v_mfma_f32_16x16x32_bf16 v[4:7], v[170:173], v[214:217], v[4:7]
	v_mfma_f32_16x16x32_bf16 v[56:59], v[166:169], v[194:197], v[56:59]
	v_mfma_f32_16x16x32_bf16 v[52:55], v[186:189], v[194:197], v[52:55]
	v_mfma_f32_16x16x32_bf16 v[40:43], v[166:169], v[202:205], v[40:43]
	v_mfma_f32_16x16x32_bf16 v[36:39], v[186:189], v[202:205], v[36:39]
	v_mfma_f32_16x16x32_bf16 v[24:27], v[166:169], v[210:213], v[24:27]
	v_mfma_f32_16x16x32_bf16 v[20:23], v[186:189], v[210:213], v[20:23]
	v_mfma_f32_16x16x32_bf16 v[8:11], v[166:169], v[218:221], v[8:11]
	v_mfma_f32_16x16x32_bf16 v[4:7], v[186:189], v[218:221], v[4:7]
	s_barrier
	s_add_i32 s63, s63, 2
	s_add_u32 s28, s28, 0x100
	s_addc_u32 s29, s29, 0
	s_cmp_gt_u32 s63, 13
	s_mov_b64 s[42:43], s[44:45]

.LBB0_500:
	s_add_u32 s44, s42, 0x100
	s_addc_u32 s45, s43, 0
	s_cmp_eq_u32 s63, 12
	s_cselect_b32 s50, s26, s44
	s_cselect_b32 s51, s5, s45
	s_cselect_b32 s48, s27, s28
	s_cselect_b32 s49, s23, s29
	s_add_u32 s46, s42, 0x80
	s_addc_u32 s47, s43, 0
	s_mov_b32 m0, s60
	s_add_u32 s42, s42, 0x40080
	s_addc_u32 s43, s43, 0
	global_load_lds_dwordx4 v144, s[46:47]
	s_mov_b32 m0, s61
	ds_read_b128 v[146:149], v240
	global_load_lds_dwordx4 v140, s[46:47]
	ds_read_b128 v[150:153], v240 offset:1024
	ds_read_b128 v[154:157], v240 offset:2048
	ds_read_b128 v[158:161], v240 offset:3072
	ds_read_b128 v[162:165], v240 offset:16384
	ds_read_b128 v[166:169], v240 offset:17408
	ds_read_b128 v[170:173], v240 offset:18432
	ds_read_b128 v[186:189], v240 offset:19456
	s_add_i32 m0, s56, 0xc000
	ds_read_b128 v[190:193], v132
	global_load_lds_dwordx4 v144, s[42:43]
	s_add_i32 m0, s56, 0xe000
	ds_read_b128 v[194:197], v132 offset:1024
	global_load_lds_dwordx4 v140, s[42:43]
	ds_read_b128 v[198:201], v132 offset:2048
	ds_read_b128 v[202:205], v132 offset:3072
	ds_read_b128 v[206:209], v132 offset:4096
	ds_read_b128 v[210:213], v132 offset:5120
	ds_read_b128 v[214:217], v132 offset:6144
	ds_read_b128 v[218:221], v132 offset:7168
	s_waitcnt vmcnt(8)
	s_waitcnt lgkmcnt(8)
	s_barrier
	s_waitcnt lgkmcnt(0)
	v_mfma_f32_16x16x32_bf16 v[128:131], v[146:149], v[190:193], v[128:131]
	v_mfma_f32_16x16x32_bf16 v[124:127], v[154:157], v[190:193], v[124:127]
	v_mfma_f32_16x16x32_bf16 v[112:115], v[146:149], v[198:201], v[112:115]
	v_mfma_f32_16x16x32_bf16 v[108:111], v[154:157], v[198:201], v[108:111]
	v_mfma_f32_16x16x32_bf16 v[96:99], v[146:149], v[206:209], v[96:99]
	v_mfma_f32_16x16x32_bf16 v[92:95], v[154:157], v[206:209], v[92:95]
	v_mfma_f32_16x16x32_bf16 v[80:83], v[146:149], v[214:217], v[80:83]
	v_mfma_f32_16x16x32_bf16 v[76:79], v[154:157], v[214:217], v[76:79]
	v_mfma_f32_16x16x32_bf16 v[128:131], v[150:153], v[194:197], v[128:131]
	v_mfma_f32_16x16x32_bf16 v[124:127], v[158:161], v[194:197], v[124:127]
	v_mfma_f32_16x16x32_bf16 v[112:115], v[150:153], v[202:205], v[112:115]
	v_mfma_f32_16x16x32_bf16 v[108:111], v[158:161], v[202:205], v[108:111]
	v_mfma_f32_16x16x32_bf16 v[96:99], v[150:153], v[210:213], v[96:99]
	v_mfma_f32_16x16x32_bf16 v[92:95], v[158:161], v[210:213], v[92:95]
	v_mfma_f32_16x16x32_bf16 v[80:83], v[150:153], v[218:221], v[80:83]
	v_mfma_f32_16x16x32_bf16 v[76:79], v[158:161], v[218:221], v[76:79]
	v_mfma_f32_16x16x32_bf16 v[120:123], v[162:165], v[190:193], v[120:123]
	v_mfma_f32_16x16x32_bf16 v[116:119], v[170:173], v[190:193], v[116:119]
	v_mfma_f32_16x16x32_bf16 v[104:107], v[162:165], v[198:201], v[104:107]
	v_mfma_f32_16x16x32_bf16 v[100:103], v[170:173], v[198:201], v[100:103]
	v_mfma_f32_16x16x32_bf16 v[88:91], v[162:165], v[206:209], v[88:91]
	v_mfma_f32_16x16x32_bf16 v[84:87], v[170:173], v[206:209], v[84:87]
	v_mfma_f32_16x16x32_bf16 v[72:75], v[162:165], v[214:217], v[72:75]
	v_mfma_f32_16x16x32_bf16 v[68:71], v[170:173], v[214:217], v[68:71]
	v_mfma_f32_16x16x32_bf16 v[120:123], v[166:169], v[194:197], v[120:123]
	v_mfma_f32_16x16x32_bf16 v[116:119], v[186:189], v[194:197], v[116:119]
	v_mfma_f32_16x16x32_bf16 v[104:107], v[166:169], v[202:205], v[104:107]
	v_mfma_f32_16x16x32_bf16 v[100:103], v[186:189], v[202:205], v[100:103]
	v_mfma_f32_16x16x32_bf16 v[88:91], v[166:169], v[210:213], v[88:91]
	v_mfma_f32_16x16x32_bf16 v[84:87], v[186:189], v[210:213], v[84:87]
	v_mfma_f32_16x16x32_bf16 v[72:75], v[166:169], v[218:221], v[72:75]
	v_mfma_f32_16x16x32_bf16 v[68:71], v[186:189], v[218:221], v[68:71]
	s_barrier
	s_add_i32 m0, s69, 0x10000
	s_add_u32 s42, s48, 0x40000
	s_addc_u32 s43, s49, 0
	global_load_lds_dwordx4 v142, s[48:49]
	s_add_i32 m0, s69, 0x12000
	ds_read_b128 v[190:193], v132 offset:16384
	global_load_lds_dwordx4 v0, s[48:49]
	s_add_i32 m0, s69, 0x14000
	ds_read_b128 v[194:197], v132 offset:17408
	global_load_lds_dwordx4 v142, s[42:43]
	s_add_i32 m0, s69, 0x16000
	ds_read_b128 v[198:201], v132 offset:18432
	global_load_lds_dwordx4 v0, s[42:43]
	ds_read_b128 v[202:205], v132 offset:19456
	ds_read_b128 v[206:209], v132 offset:20480
	ds_read_b128 v[210:213], v132 offset:21504
	ds_read_b128 v[214:217], v132 offset:22528
	ds_read_b128 v[218:221], v132 offset:23552
	s_waitcnt vmcnt(6)
	s_waitcnt lgkmcnt(0)
	s_barrier
	s_waitcnt lgkmcnt(0)
	v_mfma_f32_16x16x32_bf16 v[64:67], v[146:149], v[190:193], v[64:67]
	v_mfma_f32_16x16x32_bf16 v[60:63], v[154:157], v[190:193], v[60:63]
	v_mfma_f32_16x16x32_bf16 v[48:51], v[146:149], v[198:201], v[48:51]
	v_mfma_f32_16x16x32_bf16 v[44:47], v[154:157], v[198:201], v[44:47]
	v_mfma_f32_16x16x32_bf16 v[32:35], v[146:149], v[206:209], v[32:35]
	v_mfma_f32_16x16x32_bf16 v[28:31], v[154:157], v[206:209], v[28:31]
	v_mfma_f32_16x16x32_bf16 v[16:19], v[146:149], v[214:217], v[16:19]
	v_mfma_f32_16x16x32_bf16 v[12:15], v[154:157], v[214:217], v[12:15]
	v_mfma_f32_16x16x32_bf16 v[64:67], v[150:153], v[194:197], v[64:67]
	v_mfma_f32_16x16x32_bf16 v[60:63], v[158:161], v[194:197], v[60:63]
	v_mfma_f32_16x16x32_bf16 v[48:51], v[150:153], v[202:205], v[48:51]
	v_mfma_f32_16x16x32_bf16 v[44:47], v[158:161], v[202:205], v[44:47]
	v_mfma_f32_16x16x32_bf16 v[32:35], v[150:153], v[210:213], v[32:35]
	v_mfma_f32_16x16x32_bf16 v[28:31], v[158:161], v[210:213], v[28:31]
	v_mfma_f32_16x16x32_bf16 v[16:19], v[150:153], v[218:221], v[16:19]
	v_mfma_f32_16x16x32_bf16 v[12:15], v[158:161], v[218:221], v[12:15]
	v_mfma_f32_16x16x32_bf16 v[56:59], v[162:165], v[190:193], v[56:59]
	v_mfma_f32_16x16x32_bf16 v[52:55], v[170:173], v[190:193], v[52:55]
	v_mfma_f32_16x16x32_bf16 v[40:43], v[162:165], v[198:201], v[40:43]
	v_mfma_f32_16x16x32_bf16 v[36:39], v[170:173], v[198:201], v[36:39]
	v_mfma_f32_16x16x32_bf16 v[24:27], v[162:165], v[206:209], v[24:27]
	v_mfma_f32_16x16x32_bf16 v[20:23], v[170:173], v[206:209], v[20:23]
	v_mfma_f32_16x16x32_bf16 v[8:11], v[162:165], v[214:217], v[8:11]
	v_mfma_f32_16x16x32_bf16 v[4:7], v[170:173], v[214:217], v[4:7]
	v_mfma_f32_16x16x32_bf16 v[56:59], v[166:169], v[194:197], v[56:59]
	v_mfma_f32_16x16x32_bf16 v[52:55], v[186:189], v[194:197], v[52:55]
	v_mfma_f32_16x16x32_bf16 v[40:43], v[166:169], v[202:205], v[40:43]
	v_mfma_f32_16x16x32_bf16 v[36:39], v[186:189], v[202:205], v[36:39]
	v_mfma_f32_16x16x32_bf16 v[24:27], v[166:169], v[210:213], v[24:27]
	v_mfma_f32_16x16x32_bf16 v[20:23], v[186:189], v[210:213], v[20:23]
	v_mfma_f32_16x16x32_bf16 v[8:11], v[166:169], v[218:221], v[8:11]
	v_mfma_f32_16x16x32_bf16 v[4:7], v[186:189], v[218:221], v[4:7]
	s_barrier
	s_mov_b32 m0, s56
	s_add_u32 s42, s50, 0x40000
	s_addc_u32 s43, s51, 0
	global_load_lds_dwordx4 v144, s[50:51]
	s_mov_b32 m0, s57
	ds_read_b128 v[146:149], v240 offset:32768
	global_load_lds_dwordx4 v140, s[50:51]
	ds_read_b128 v[150:153], v240 offset:33792
	ds_read_b128 v[154:157], v240 offset:34816
	ds_read_b128 v[158:161], v240 offset:35840
	ds_read_b128 v[162:165], v240 offset:49152
	ds_read_b128 v[166:169], v240 offset:50176
	ds_read_b128 v[170:173], v240 offset:51200
	ds_read_b128 v[186:189], v240 offset:52224
	s_mov_b32 m0, s58
	ds_read_b128 v[190:193], v132 offset:32768
	global_load_lds_dwordx4 v144, s[42:43]
	s_mov_b32 m0, s59
	ds_read_b128 v[194:197], v132 offset:33792
	global_load_lds_dwordx4 v140, s[42:43]
	ds_read_b128 v[198:201], v132 offset:34816
	ds_read_b128 v[202:205], v132 offset:35840
	ds_read_b128 v[206:209], v132 offset:36864
	ds_read_b128 v[210:213], v132 offset:37888
	ds_read_b128 v[214:217], v132 offset:38912
	ds_read_b128 v[218:221], v132 offset:39936
	s_waitcnt vmcnt(8)
	s_waitcnt lgkmcnt(8)
	s_barrier
	s_waitcnt lgkmcnt(0)
	v_mfma_f32_16x16x32_bf16 v[128:131], v[146:149], v[190:193], v[128:131]
	v_mfma_f32_16x16x32_bf16 v[124:127], v[154:157], v[190:193], v[124:127]
	v_mfma_f32_16x16x32_bf16 v[112:115], v[146:149], v[198:201], v[112:115]
	v_mfma_f32_16x16x32_bf16 v[108:111], v[154:157], v[198:201], v[108:111]
	v_mfma_f32_16x16x32_bf16 v[96:99], v[146:149], v[206:209], v[96:99]
	v_mfma_f32_16x16x32_bf16 v[92:95], v[154:157], v[206:209], v[92:95]
	v_mfma_f32_16x16x32_bf16 v[80:83], v[146:149], v[214:217], v[80:83]
	v_mfma_f32_16x16x32_bf16 v[76:79], v[154:157], v[214:217], v[76:79]
	v_mfma_f32_16x16x32_bf16 v[128:131], v[150:153], v[194:197], v[128:131]
	v_mfma_f32_16x16x32_bf16 v[124:127], v[158:161], v[194:197], v[124:127]
	v_mfma_f32_16x16x32_bf16 v[112:115], v[150:153], v[202:205], v[112:115]
	v_mfma_f32_16x16x32_bf16 v[108:111], v[158:161], v[202:205], v[108:111]
	v_mfma_f32_16x16x32_bf16 v[96:99], v[150:153], v[210:213], v[96:99]
	v_mfma_f32_16x16x32_bf16 v[92:95], v[158:161], v[210:213], v[92:95]
	v_mfma_f32_16x16x32_bf16 v[80:83], v[150:153], v[218:221], v[80:83]
	v_mfma_f32_16x16x32_bf16 v[76:79], v[158:161], v[218:221], v[76:79]
	v_mfma_f32_16x16x32_bf16 v[120:123], v[162:165], v[190:193], v[120:123]
	v_mfma_f32_16x16x32_bf16 v[116:119], v[170:173], v[190:193], v[116:119]
	v_mfma_f32_16x16x32_bf16 v[104:107], v[162:165], v[198:201], v[104:107]
	v_mfma_f32_16x16x32_bf16 v[100:103], v[170:173], v[198:201], v[100:103]
	v_mfma_f32_16x16x32_bf16 v[88:91], v[162:165], v[206:209], v[88:91]
	v_mfma_f32_16x16x32_bf16 v[84:87], v[170:173], v[206:209], v[84:87]
	v_mfma_f32_16x16x32_bf16 v[72:75], v[162:165], v[214:217], v[72:75]
	v_mfma_f32_16x16x32_bf16 v[68:71], v[170:173], v[214:217], v[68:71]
	v_mfma_f32_16x16x32_bf16 v[120:123], v[166:169], v[194:197], v[120:123]
	v_mfma_f32_16x16x32_bf16 v[116:119], v[186:189], v[194:197], v[116:119]
	v_mfma_f32_16x16x32_bf16 v[104:107], v[166:169], v[202:205], v[104:107]
	v_mfma_f32_16x16x32_bf16 v[100:103], v[186:189], v[202:205], v[100:103]
	v_mfma_f32_16x16x32_bf16 v[88:91], v[166:169], v[210:213], v[88:91]
	v_mfma_f32_16x16x32_bf16 v[84:87], v[186:189], v[210:213], v[84:87]
	v_mfma_f32_16x16x32_bf16 v[72:75], v[166:169], v[218:221], v[72:75]
	v_mfma_f32_16x16x32_bf16 v[68:71], v[186:189], v[218:221], v[68:71]
	s_barrier
	s_add_u32 s42, s48, 0x80
	s_addc_u32 s43, s49, 0
	s_add_i32 m0, s69, 0x18000
	s_add_u32 s46, s48, 0x40080
	s_addc_u32 s47, s49, 0
	global_load_lds_dwordx4 v142, s[42:43]
	s_add_i32 m0, s69, 0x1a000
	ds_read_b128 v[190:193], v132 offset:49152
	global_load_lds_dwordx4 v0, s[42:43]
	s_add_i32 m0, s69, 0x1c000
	ds_read_b128 v[194:197], v132 offset:50176
	global_load_lds_dwordx4 v142, s[46:47]
	s_add_i32 m0, s69, 0x1e000
	ds_read_b128 v[198:201], v132 offset:51200
	global_load_lds_dwordx4 v0, s[46:47]
	ds_read_b128 v[202:205], v132 offset:52224
	ds_read_b128 v[206:209], v132 offset:53248
	ds_read_b128 v[210:213], v132 offset:54272
	ds_read_b128 v[214:217], v132 offset:55296
	ds_read_b128 v[218:221], v132 offset:56320
	s_waitcnt vmcnt(6)
	s_waitcnt lgkmcnt(0)
	s_barrier
	s_waitcnt lgkmcnt(0)
	v_mfma_f32_16x16x32_bf16 v[64:67], v[146:149], v[190:193], v[64:67]
	v_mfma_f32_16x16x32_bf16 v[60:63], v[154:157], v[190:193], v[60:63]
	v_mfma_f32_16x16x32_bf16 v[48:51], v[146:149], v[198:201], v[48:51]
	v_mfma_f32_16x16x32_bf16 v[44:47], v[154:157], v[198:201], v[44:47]
	v_mfma_f32_16x16x32_bf16 v[32:35], v[146:149], v[206:209], v[32:35]
	v_mfma_f32_16x16x32_bf16 v[28:31], v[154:157], v[206:209], v[28:31]
	v_mfma_f32_16x16x32_bf16 v[16:19], v[146:149], v[214:217], v[16:19]
	v_mfma_f32_16x16x32_bf16 v[12:15], v[154:157], v[214:217], v[12:15]
	v_mfma_f32_16x16x32_bf16 v[64:67], v[150:153], v[194:197], v[64:67]
	v_mfma_f32_16x16x32_bf16 v[60:63], v[158:161], v[194:197], v[60:63]
	v_mfma_f32_16x16x32_bf16 v[48:51], v[150:153], v[202:205], v[48:51]
	v_mfma_f32_16x16x32_bf16 v[44:47], v[158:161], v[202:205], v[44:47]
	v_mfma_f32_16x16x32_bf16 v[32:35], v[150:153], v[210:213], v[32:35]
	v_mfma_f32_16x16x32_bf16 v[28:31], v[158:161], v[210:213], v[28:31]
	v_mfma_f32_16x16x32_bf16 v[16:19], v[150:153], v[218:221], v[16:19]
	v_mfma_f32_16x16x32_bf16 v[12:15], v[158:161], v[218:221], v[12:15]
	v_mfma_f32_16x16x32_bf16 v[56:59], v[162:165], v[190:193], v[56:59]
	v_mfma_f32_16x16x32_bf16 v[52:55], v[170:173], v[190:193], v[52:55]
	v_mfma_f32_16x16x32_bf16 v[40:43], v[162:165], v[198:201], v[40:43]
	v_mfma_f32_16x16x32_bf16 v[36:39], v[170:173], v[198:201], v[36:39]
	v_mfma_f32_16x16x32_bf16 v[24:27], v[162:165], v[206:209], v[24:27]
	v_mfma_f32_16x16x32_bf16 v[20:23], v[170:173], v[206:209], v[20:23]
	v_mfma_f32_16x16x32_bf16 v[8:11], v[162:165], v[214:217], v[8:11]
	v_mfma_f32_16x16x32_bf16 v[4:7], v[170:173], v[214:217], v[4:7]
	v_mfma_f32_16x16x32_bf16 v[56:59], v[166:169], v[194:197], v[56:59]
	v_mfma_f32_16x16x32_bf16 v[52:55], v[186:189], v[194:197], v[52:55]
	v_mfma_f32_16x16x32_bf16 v[40:43], v[166:169], v[202:205], v[40:43]
	v_mfma_f32_16x16x32_bf16 v[36:39], v[186:189], v[202:205], v[36:39]
	v_mfma_f32_16x16x32_bf16 v[24:27], v[166:169], v[210:213], v[24:27]
	v_mfma_f32_16x16x32_bf16 v[20:23], v[186:189], v[210:213], v[20:23]
	v_mfma_f32_16x16x32_bf16 v[8:11], v[166:169], v[218:221], v[8:11]
	v_mfma_f32_16x16x32_bf16 v[4:7], v[186:189], v[218:221], v[4:7]
	s_barrier
	s_add_i32 s63, s63, 2
	s_add_u32 s28, s28, 0x100
	s_addc_u32 s29, s29, 0
	s_cmp_gt_u32 s63, 13
	s_mov_b64 s[42:43], s[44:45]
	s_cbranch_scc0 .LBB0_500
	s_andn2_b64 vcc, s[14:15], s[40:41]
	s_and_b64 vcc, exec, vcc
	s_cbranch_vccz .LBB0_503
	s_barrier
.LBB0_503:
	s_setprio 0
	v_mov_b32_e32 v139, v174
	s_lshl_b32 s5, s9, 8
	s_add_i32 s5, s5, s70
	v_and_or_b32 v138, v139, 15, s5
	s_lshl_b32 s5, s8, 7
	v_ashrrev_i32_e32 v139, 1, v139
	s_or_b32 s5, s5, s71
	v_and_b32_e32 v139, -8, v139
	v_add_u32_e32 v148, s5, v139
	v_ashrrev_i32_e32 v149, 31, v148
	v_mov_b64_e32 v[146:147], s[0:1]
	v_ashrrev_i32_e32 v139, 31, v138
	v_mad_i64_i32 v[150:151], s[8:9], v138, s73, v[146:147]
	v_lshlrev_b64 v[148:149], 1, v[148:149]
	v_lshl_add_u64 v[152:153], v[150:151], 0, v[148:149]
	v_lshl_add_u64 v[150:151], v[138:139], 2, s[2:3]
	global_load_dword v206, v[150:151], off
	global_load_dword v208, v[150:151], off offset:64
	global_load_dword v210, v[150:151], off offset:128
	global_load_dword v212, v[150:151], off offset:192
	global_load_dword v214, v[150:151], off offset:512
	global_load_dword v216, v[150:151], off offset:576
	global_load_dword v218, v[150:151], off offset:640
	global_load_dword v220, v[150:151], off offset:704
	s_mov_b64 s[42:43], -1
	s_andn2_b64 vcc, exec, s[40:41]
	v_mov_b32_e32 v154, 0xbfb8aa3b
	v_mov_b32_e32 v155, 0xbfb8aa3b
	v_mov_b32_e32 v156, 1.0
	v_mov_b32_e32 v157, 1.0
	v_mov_b32_e32 v159, 0
	s_waitcnt vmcnt(0)
	v_pk_mul_f32 v[128:129], v[128:129], v[206:207] op_sel_hi:[1,0]
	v_pk_mul_f32 v[130:131], v[130:131], v[206:207] op_sel_hi:[1,0]
	v_pk_mul_f32 v[124:125], v[124:125], v[206:207] op_sel_hi:[1,0]
	v_pk_mul_f32 v[126:127], v[126:127], v[206:207] op_sel_hi:[1,0]
	v_pk_mul_f32 v[162:163], v[128:129], v[154:155]
	v_pk_mul_f32 v[164:165], v[130:131], v[154:155]
	v_pk_mul_f32 v[166:167], v[124:125], v[154:155]
	v_pk_mul_f32 v[168:169], v[126:127], v[154:155]
	v_exp_f32_e32 v162, v162
	v_exp_f32_e32 v163, v163
	v_exp_f32_e32 v164, v164
	v_exp_f32_e32 v165, v165
	v_exp_f32_e32 v166, v166
	v_exp_f32_e32 v167, v167
	v_exp_f32_e32 v168, v168
	v_exp_f32_e32 v169, v169
	v_pk_mul_f32 v[120:121], v[120:121], v[206:207] op_sel_hi:[1,0]
	v_pk_mul_f32 v[122:123], v[122:123], v[206:207] op_sel_hi:[1,0]
	v_pk_mul_f32 v[116:117], v[116:117], v[206:207] op_sel_hi:[1,0]
	v_pk_mul_f32 v[118:119], v[118:119], v[206:207] op_sel_hi:[1,0]
	v_pk_add_f32 v[162:163], v[162:163], v[156:157]
	v_pk_add_f32 v[164:165], v[164:165], v[156:157]
	v_pk_add_f32 v[166:167], v[166:167], v[156:157]
	v_pk_add_f32 v[168:169], v[168:169], v[156:157]
	v_rcp_f32_e32 v162, v162
	v_rcp_f32_e32 v163, v163
	v_rcp_f32_e32 v164, v164
	v_rcp_f32_e32 v165, v165
	v_rcp_f32_e32 v166, v166
	v_rcp_f32_e32 v167, v167
	v_rcp_f32_e32 v168, v168
	v_rcp_f32_e32 v169, v169
	v_pk_mul_f32 v[128:129], v[128:129], v[120:121]
	v_pk_mul_f32 v[130:131], v[130:131], v[122:123]
	v_pk_mul_f32 v[124:125], v[124:125], v[116:117]
	v_pk_mul_f32 v[126:127], v[126:127], v[118:119]
	v_pk_mul_f32 v[128:129], v[128:129], v[162:163]
	v_pk_mul_f32 v[130:131], v[130:131], v[164:165]
	v_pk_mul_f32 v[124:125], v[124:125], v[166:167]
	v_pk_mul_f32 v[126:127], v[126:127], v[168:169]
	v_cvt_pk_bf16_f32 v170, v128, v129
	v_cvt_pk_bf16_f32 v171, v130, v131
	v_cvt_pk_bf16_f32 v172, v124, v125
	v_cvt_pk_bf16_f32 v173, v126, v127
	global_store_dwordx4 v[152:153], v[170:173], off
	v_pk_mul_f32 v[112:113], v[112:113], v[208:209] op_sel_hi:[1,0]
	v_pk_mul_f32 v[114:115], v[114:115], v[208:209] op_sel_hi:[1,0]
	v_pk_mul_f32 v[108:109], v[108:109], v[208:209] op_sel_hi:[1,0]
	v_pk_mul_f32 v[110:111], v[110:111], v[208:209] op_sel_hi:[1,0]
	v_pk_mul_f32 v[162:163], v[112:113], v[154:155]
	v_pk_mul_f32 v[164:165], v[114:115], v[154:155]
	v_pk_mul_f32 v[166:167], v[108:109], v[154:155]
	v_pk_mul_f32 v[168:169], v[110:111], v[154:155]
	v_exp_f32_e32 v162, v162
	v_exp_f32_e32 v163, v163
	v_exp_f32_e32 v164, v164
	v_exp_f32_e32 v165, v165
	v_exp_f32_e32 v166, v166
	v_exp_f32_e32 v167, v167
	v_exp_f32_e32 v168, v168
	v_exp_f32_e32 v169, v169
	v_pk_mul_f32 v[104:105], v[104:105], v[208:209] op_sel_hi:[1,0]
	v_pk_mul_f32 v[106:107], v[106:107], v[208:209] op_sel_hi:[1,0]
	v_pk_mul_f32 v[100:101], v[100:101], v[208:209] op_sel_hi:[1,0]
	v_pk_mul_f32 v[102:103], v[102:103], v[208:209] op_sel_hi:[1,0]
	v_pk_add_f32 v[162:163], v[162:163], v[156:157]
	v_pk_add_f32 v[164:165], v[164:165], v[156:157]
	v_pk_add_f32 v[166:167], v[166:167], v[156:157]
	v_pk_add_f32 v[168:169], v[168:169], v[156:157]
	v_rcp_f32_e32 v162, v162
	v_rcp_f32_e32 v163, v163
	v_rcp_f32_e32 v164, v164
	v_rcp_f32_e32 v165, v165
	v_rcp_f32_e32 v166, v166
	v_rcp_f32_e32 v167, v167
	v_rcp_f32_e32 v168, v168
	v_rcp_f32_e32 v169, v169
	v_pk_mul_f32 v[112:113], v[112:113], v[104:105]
	v_pk_mul_f32 v[114:115], v[114:115], v[106:107]
	v_pk_mul_f32 v[108:109], v[108:109], v[100:101]
	v_pk_mul_f32 v[110:111], v[110:111], v[102:103]
	v_pk_mul_f32 v[112:113], v[112:113], v[162:163]
	v_pk_mul_f32 v[114:115], v[114:115], v[164:165]
	v_pk_mul_f32 v[108:109], v[108:109], v[166:167]
	v_pk_mul_f32 v[110:111], v[110:111], v[168:169]
	v_cvt_pk_bf16_f32 v186, v112, v113
	v_cvt_pk_bf16_f32 v187, v114, v115
	v_cvt_pk_bf16_f32 v188, v108, v109
	v_cvt_pk_bf16_f32 v189, v110, v111
	v_mov_b32_e32 v158, 0x16000
	v_lshl_add_u64 v[160:161], v[152:153], 0, v[158:159]
	global_store_dwordx4 v[160:161], v[186:189], off
	v_pk_mul_f32 v[96:97], v[96:97], v[210:211] op_sel_hi:[1,0]
	v_pk_mul_f32 v[98:99], v[98:99], v[210:211] op_sel_hi:[1,0]
	v_pk_mul_f32 v[92:93], v[92:93], v[210:211] op_sel_hi:[1,0]
	v_pk_mul_f32 v[94:95], v[94:95], v[210:211] op_sel_hi:[1,0]
	v_pk_mul_f32 v[162:163], v[96:97], v[154:155]
	v_pk_mul_f32 v[164:165], v[98:99], v[154:155]
	v_pk_mul_f32 v[166:167], v[92:93], v[154:155]
	v_pk_mul_f32 v[168:169], v[94:95], v[154:155]
	v_exp_f32_e32 v162, v162
	v_exp_f32_e32 v163, v163
	v_exp_f32_e32 v164, v164
	v_exp_f32_e32 v165, v165
	v_exp_f32_e32 v166, v166
	v_exp_f32_e32 v167, v167
	v_exp_f32_e32 v168, v168
	v_exp_f32_e32 v169, v169
	v_pk_mul_f32 v[88:89], v[88:89], v[210:211] op_sel_hi:[1,0]
	v_pk_mul_f32 v[90:91], v[90:91], v[210:211] op_sel_hi:[1,0]
	v_pk_mul_f32 v[84:85], v[84:85], v[210:211] op_sel_hi:[1,0]
	v_pk_mul_f32 v[86:87], v[86:87], v[210:211] op_sel_hi:[1,0]
	v_pk_add_f32 v[162:163], v[162:163], v[156:157]
	v_pk_add_f32 v[164:165], v[164:165], v[156:157]
	v_pk_add_f32 v[166:167], v[166:167], v[156:157]
	v_pk_add_f32 v[168:169], v[168:169], v[156:157]
	v_rcp_f32_e32 v162, v162
	v_rcp_f32_e32 v163, v163
	v_rcp_f32_e32 v164, v164
	v_rcp_f32_e32 v165, v165
	v_rcp_f32_e32 v166, v166
	v_rcp_f32_e32 v167, v167
	v_rcp_f32_e32 v168, v168
	v_rcp_f32_e32 v169, v169
	v_pk_mul_f32 v[96:97], v[96:97], v[88:89]
	v_pk_mul_f32 v[98:99], v[98:99], v[90:91]
	v_pk_mul_f32 v[92:93], v[92:93], v[84:85]
	v_pk_mul_f32 v[94:95], v[94:95], v[86:87]
	v_pk_mul_f32 v[96:97], v[96:97], v[162:163]
	v_pk_mul_f32 v[98:99], v[98:99], v[164:165]
	v_pk_mul_f32 v[92:93], v[92:93], v[166:167]
	v_pk_mul_f32 v[94:95], v[94:95], v[168:169]
	v_cvt_pk_bf16_f32 v170, v96, v97
	v_cvt_pk_bf16_f32 v171, v98, v99
	v_cvt_pk_bf16_f32 v172, v92, v93
	v_cvt_pk_bf16_f32 v173, v94, v95
	v_mov_b32_e32 v158, 0x2c000
	v_lshl_add_u64 v[160:161], v[152:153], 0, v[158:159]
	global_store_dwordx4 v[160:161], v[170:173], off
	v_pk_mul_f32 v[80:81], v[80:81], v[212:213] op_sel_hi:[1,0]
	v_pk_mul_f32 v[82:83], v[82:83], v[212:213] op_sel_hi:[1,0]
	v_pk_mul_f32 v[76:77], v[76:77], v[212:213] op_sel_hi:[1,0]
	v_pk_mul_f32 v[78:79], v[78:79], v[212:213] op_sel_hi:[1,0]
	v_pk_mul_f32 v[162:163], v[80:81], v[154:155]
	v_pk_mul_f32 v[164:165], v[82:83], v[154:155]
	v_pk_mul_f32 v[166:167], v[76:77], v[154:155]
	v_pk_mul_f32 v[168:169], v[78:79], v[154:155]
	v_exp_f32_e32 v162, v162
	v_exp_f32_e32 v163, v163
	v_exp_f32_e32 v164, v164
	v_exp_f32_e32 v165, v165
	v_exp_f32_e32 v166, v166
	v_exp_f32_e32 v167, v167
	v_exp_f32_e32 v168, v168
	v_exp_f32_e32 v169, v169
	v_pk_mul_f32 v[72:73], v[72:73], v[212:213] op_sel_hi:[1,0]
	v_pk_mul_f32 v[74:75], v[74:75], v[212:213] op_sel_hi:[1,0]
	v_pk_mul_f32 v[68:69], v[68:69], v[212:213] op_sel_hi:[1,0]
	v_pk_mul_f32 v[70:71], v[70:71], v[212:213] op_sel_hi:[1,0]
	v_pk_add_f32 v[162:163], v[162:163], v[156:157]
	v_pk_add_f32 v[164:165], v[164:165], v[156:157]
	v_pk_add_f32 v[166:167], v[166:167], v[156:157]
	v_pk_add_f32 v[168:169], v[168:169], v[156:157]
	v_rcp_f32_e32 v162, v162
	v_rcp_f32_e32 v163, v163
	v_rcp_f32_e32 v164, v164
	v_rcp_f32_e32 v165, v165
	v_rcp_f32_e32 v166, v166
	v_rcp_f32_e32 v167, v167
	v_rcp_f32_e32 v168, v168
	v_rcp_f32_e32 v169, v169
	v_pk_mul_f32 v[80:81], v[80:81], v[72:73]
	v_pk_mul_f32 v[82:83], v[82:83], v[74:75]
	v_pk_mul_f32 v[76:77], v[76:77], v[68:69]
	v_pk_mul_f32 v[78:79], v[78:79], v[70:71]
	v_pk_mul_f32 v[80:81], v[80:81], v[162:163]
	v_pk_mul_f32 v[82:83], v[82:83], v[164:165]
	v_pk_mul_f32 v[76:77], v[76:77], v[166:167]
	v_pk_mul_f32 v[78:79], v[78:79], v[168:169]
	v_cvt_pk_bf16_f32 v186, v80, v81
	v_cvt_pk_bf16_f32 v187, v82, v83
	v_cvt_pk_bf16_f32 v188, v76, v77
	v_cvt_pk_bf16_f32 v189, v78, v79
	v_mov_b32_e32 v158, 0x42000
	v_lshl_add_u64 v[160:161], v[152:153], 0, v[158:159]
	global_store_dwordx4 v[160:161], v[186:189], off
	v_pk_mul_f32 v[64:65], v[64:65], v[214:215] op_sel_hi:[1,0]
	v_pk_mul_f32 v[66:67], v[66:67], v[214:215] op_sel_hi:[1,0]
	v_pk_mul_f32 v[60:61], v[60:61], v[214:215] op_sel_hi:[1,0]
	v_pk_mul_f32 v[62:63], v[62:63], v[214:215] op_sel_hi:[1,0]
	v_pk_mul_f32 v[162:163], v[64:65], v[154:155]
	v_pk_mul_f32 v[164:165], v[66:67], v[154:155]
	v_pk_mul_f32 v[166:167], v[60:61], v[154:155]
	v_pk_mul_f32 v[168:169], v[62:63], v[154:155]
	v_exp_f32_e32 v162, v162
	v_exp_f32_e32 v163, v163
	v_exp_f32_e32 v164, v164
	v_exp_f32_e32 v165, v165
	v_exp_f32_e32 v166, v166
	v_exp_f32_e32 v167, v167
	v_exp_f32_e32 v168, v168
	v_exp_f32_e32 v169, v169
	v_pk_mul_f32 v[56:57], v[56:57], v[214:215] op_sel_hi:[1,0]
	v_pk_mul_f32 v[58:59], v[58:59], v[214:215] op_sel_hi:[1,0]
	v_pk_mul_f32 v[52:53], v[52:53], v[214:215] op_sel_hi:[1,0]
	v_pk_mul_f32 v[54:55], v[54:55], v[214:215] op_sel_hi:[1,0]
	v_pk_add_f32 v[162:163], v[162:163], v[156:157]
	v_pk_add_f32 v[164:165], v[164:165], v[156:157]
	v_pk_add_f32 v[166:167], v[166:167], v[156:157]
	v_pk_add_f32 v[168:169], v[168:169], v[156:157]
	v_rcp_f32_e32 v162, v162
	v_rcp_f32_e32 v163, v163
	v_rcp_f32_e32 v164, v164
	v_rcp_f32_e32 v165, v165
	v_rcp_f32_e32 v166, v166
	v_rcp_f32_e32 v167, v167
	v_rcp_f32_e32 v168, v168
	v_rcp_f32_e32 v169, v169
	v_pk_mul_f32 v[64:65], v[64:65], v[56:57]
	v_pk_mul_f32 v[66:67], v[66:67], v[58:59]
	v_pk_mul_f32 v[60:61], v[60:61], v[52:53]
	v_pk_mul_f32 v[62:63], v[62:63], v[54:55]
	v_pk_mul_f32 v[64:65], v[64:65], v[162:163]
	v_pk_mul_f32 v[66:67], v[66:67], v[164:165]
	v_pk_mul_f32 v[60:61], v[60:61], v[166:167]
	v_pk_mul_f32 v[62:63], v[62:63], v[168:169]
	v_cvt_pk_bf16_f32 v170, v64, v65
	v_cvt_pk_bf16_f32 v171, v66, v67
	v_cvt_pk_bf16_f32 v172, v60, v61
	v_cvt_pk_bf16_f32 v173, v62, v63
	v_mov_b32_e32 v158, 0xb0000
	v_lshl_add_u64 v[160:161], v[152:153], 0, v[158:159]
	global_store_dwordx4 v[160:161], v[170:173], off
	v_pk_mul_f32 v[48:49], v[48:49], v[216:217] op_sel_hi:[1,0]
	v_pk_mul_f32 v[50:51], v[50:51], v[216:217] op_sel_hi:[1,0]
	v_pk_mul_f32 v[44:45], v[44:45], v[216:217] op_sel_hi:[1,0]
	v_pk_mul_f32 v[46:47], v[46:47], v[216:217] op_sel_hi:[1,0]
	v_pk_mul_f32 v[162:163], v[48:49], v[154:155]
	v_pk_mul_f32 v[164:165], v[50:51], v[154:155]
	v_pk_mul_f32 v[166:167], v[44:45], v[154:155]
	v_pk_mul_f32 v[168:169], v[46:47], v[154:155]
	v_exp_f32_e32 v162, v162
	v_exp_f32_e32 v163, v163
	v_exp_f32_e32 v164, v164
	v_exp_f32_e32 v165, v165
	v_exp_f32_e32 v166, v166
	v_exp_f32_e32 v167, v167
	v_exp_f32_e32 v168, v168
	v_exp_f32_e32 v169, v169
	v_pk_mul_f32 v[40:41], v[40:41], v[216:217] op_sel_hi:[1,0]
	v_pk_mul_f32 v[42:43], v[42:43], v[216:217] op_sel_hi:[1,0]
	v_pk_mul_f32 v[36:37], v[36:37], v[216:217] op_sel_hi:[1,0]
	v_pk_mul_f32 v[38:39], v[38:39], v[216:217] op_sel_hi:[1,0]
	v_pk_add_f32 v[162:163], v[162:163], v[156:157]
	v_pk_add_f32 v[164:165], v[164:165], v[156:157]
	v_pk_add_f32 v[166:167], v[166:167], v[156:157]
	v_pk_add_f32 v[168:169], v[168:169], v[156:157]
	v_rcp_f32_e32 v162, v162
	v_rcp_f32_e32 v163, v163
	v_rcp_f32_e32 v164, v164
	v_rcp_f32_e32 v165, v165
	v_rcp_f32_e32 v166, v166
	v_rcp_f32_e32 v167, v167
	v_rcp_f32_e32 v168, v168
	v_rcp_f32_e32 v169, v169
	v_pk_mul_f32 v[48:49], v[48:49], v[40:41]
	v_pk_mul_f32 v[50:51], v[50:51], v[42:43]
	v_pk_mul_f32 v[44:45], v[44:45], v[36:37]
	v_pk_mul_f32 v[46:47], v[46:47], v[38:39]
	v_pk_mul_f32 v[48:49], v[48:49], v[162:163]
	v_pk_mul_f32 v[50:51], v[50:51], v[164:165]
	v_pk_mul_f32 v[44:45], v[44:45], v[166:167]
	v_pk_mul_f32 v[46:47], v[46:47], v[168:169]
	v_cvt_pk_bf16_f32 v186, v48, v49
	v_cvt_pk_bf16_f32 v187, v50, v51
	v_cvt_pk_bf16_f32 v188, v44, v45
	v_cvt_pk_bf16_f32 v189, v46, v47
	v_mov_b32_e32 v158, 0xc6000
	v_lshl_add_u64 v[160:161], v[152:153], 0, v[158:159]
	global_store_dwordx4 v[160:161], v[186:189], off
	v_pk_mul_f32 v[32:33], v[32:33], v[218:219] op_sel_hi:[1,0]
	v_pk_mul_f32 v[34:35], v[34:35], v[218:219] op_sel_hi:[1,0]
	v_pk_mul_f32 v[28:29], v[28:29], v[218:219] op_sel_hi:[1,0]
	v_pk_mul_f32 v[30:31], v[30:31], v[218:219] op_sel_hi:[1,0]
	v_pk_mul_f32 v[162:163], v[32:33], v[154:155]
	v_pk_mul_f32 v[164:165], v[34:35], v[154:155]
	v_pk_mul_f32 v[166:167], v[28:29], v[154:155]
	v_pk_mul_f32 v[168:169], v[30:31], v[154:155]
	v_exp_f32_e32 v162, v162
	v_exp_f32_e32 v163, v163
	v_exp_f32_e32 v164, v164
	v_exp_f32_e32 v165, v165
	v_exp_f32_e32 v166, v166
	v_exp_f32_e32 v167, v167
	v_exp_f32_e32 v168, v168
	v_exp_f32_e32 v169, v169
	v_pk_mul_f32 v[24:25], v[24:25], v[218:219] op_sel_hi:[1,0]
	v_pk_mul_f32 v[26:27], v[26:27], v[218:219] op_sel_hi:[1,0]
	v_pk_mul_f32 v[20:21], v[20:21], v[218:219] op_sel_hi:[1,0]
	v_pk_mul_f32 v[22:23], v[22:23], v[218:219] op_sel_hi:[1,0]
	v_pk_add_f32 v[162:163], v[162:163], v[156:157]
	v_pk_add_f32 v[164:165], v[164:165], v[156:157]
	v_pk_add_f32 v[166:167], v[166:167], v[156:157]
	v_pk_add_f32 v[168:169], v[168:169], v[156:157]
	v_rcp_f32_e32 v162, v162
	v_rcp_f32_e32 v163, v163
	v_rcp_f32_e32 v164, v164
	v_rcp_f32_e32 v165, v165
	v_rcp_f32_e32 v166, v166
	v_rcp_f32_e32 v167, v167
	v_rcp_f32_e32 v168, v168
	v_rcp_f32_e32 v169, v169
	v_pk_mul_f32 v[32:33], v[32:33], v[24:25]
	v_pk_mul_f32 v[34:35], v[34:35], v[26:27]
	v_pk_mul_f32 v[28:29], v[28:29], v[20:21]
	v_pk_mul_f32 v[30:31], v[30:31], v[22:23]
	v_pk_mul_f32 v[32:33], v[32:33], v[162:163]
	v_pk_mul_f32 v[34:35], v[34:35], v[164:165]
	v_pk_mul_f32 v[28:29], v[28:29], v[166:167]
	v_pk_mul_f32 v[30:31], v[30:31], v[168:169]
	v_cvt_pk_bf16_f32 v170, v32, v33
	v_cvt_pk_bf16_f32 v171, v34, v35
	v_cvt_pk_bf16_f32 v172, v28, v29
	v_cvt_pk_bf16_f32 v173, v30, v31
	v_mov_b32_e32 v158, 0xdc000
	v_lshl_add_u64 v[160:161], v[152:153], 0, v[158:159]
	global_store_dwordx4 v[160:161], v[170:173], off
	v_pk_mul_f32 v[16:17], v[16:17], v[220:221] op_sel_hi:[1,0]
	v_pk_mul_f32 v[18:19], v[18:19], v[220:221] op_sel_hi:[1,0]
	v_pk_mul_f32 v[12:13], v[12:13], v[220:221] op_sel_hi:[1,0]
	v_pk_mul_f32 v[14:15], v[14:15], v[220:221] op_sel_hi:[1,0]
	v_pk_mul_f32 v[162:163], v[16:17], v[154:155]
	v_pk_mul_f32 v[164:165], v[18:19], v[154:155]
	v_pk_mul_f32 v[166:167], v[12:13], v[154:155]
	v_pk_mul_f32 v[168:169], v[14:15], v[154:155]
	v_exp_f32_e32 v162, v162
	v_exp_f32_e32 v163, v163
	v_exp_f32_e32 v164, v164
	v_exp_f32_e32 v165, v165
	v_exp_f32_e32 v166, v166
	v_exp_f32_e32 v167, v167
	v_exp_f32_e32 v168, v168
	v_exp_f32_e32 v169, v169
	v_pk_mul_f32 v[8:9], v[8:9], v[220:221] op_sel_hi:[1,0]
	v_pk_mul_f32 v[10:11], v[10:11], v[220:221] op_sel_hi:[1,0]
	v_pk_mul_f32 v[4:5], v[4:5], v[220:221] op_sel_hi:[1,0]
	v_pk_mul_f32 v[6:7], v[6:7], v[220:221] op_sel_hi:[1,0]
	v_pk_add_f32 v[162:163], v[162:163], v[156:157]
	v_pk_add_f32 v[164:165], v[164:165], v[156:157]
	v_pk_add_f32 v[166:167], v[166:167], v[156:157]
	v_pk_add_f32 v[168:169], v[168:169], v[156:157]
	v_rcp_f32_e32 v162, v162
	v_rcp_f32_e32 v163, v163
	v_rcp_f32_e32 v164, v164
	v_rcp_f32_e32 v165, v165
	v_rcp_f32_e32 v166, v166
	v_rcp_f32_e32 v167, v167
	v_rcp_f32_e32 v168, v168
	v_rcp_f32_e32 v169, v169
	v_pk_mul_f32 v[16:17], v[16:17], v[8:9]
	v_pk_mul_f32 v[18:19], v[18:19], v[10:11]
	v_pk_mul_f32 v[12:13], v[12:13], v[4:5]
	v_pk_mul_f32 v[14:15], v[14:15], v[6:7]
	v_pk_mul_f32 v[16:17], v[16:17], v[162:163]
	v_pk_mul_f32 v[18:19], v[18:19], v[164:165]
	v_pk_mul_f32 v[12:13], v[12:13], v[166:167]
	v_pk_mul_f32 v[14:15], v[14:15], v[168:169]
	v_cvt_pk_bf16_f32 v186, v16, v17
	v_cvt_pk_bf16_f32 v187, v18, v19
	v_cvt_pk_bf16_f32 v188, v12, v13
	v_cvt_pk_bf16_f32 v189, v14, v15
	v_mov_b32_e32 v158, 0xf2000
	v_lshl_add_u64 v[160:161], v[152:153], 0, v[158:159]
	global_store_dwordx4 v[160:161], v[186:189], off
	s_cbranch_vccnz .LBB0_496
	s_branch .LBB0_495
